# y-batch rwkv scans + batched loads in rwkv fix-up tile, prep tile and conv tile staging (single wait instead of per-load waits)
# speedup vs baseline: 1.0314x; 1.0152x over previous
; __device__ __forceinline__ float bf2f(bf16_t v) { return __uint_as_float(((unsigned)v) << 16); }
; __device__ __forceinline__ bf16_t f2bf(float f) { return (bf16_t)(pack2(f, 0.f) & 0xffffu); }
; __device__ __forceinline__ int launder(int x) { asm volatile("" : "+v"(x)); return x; }
; #define MFMA(a, b, c) __builtin_amdgcn_mfma_f32_16x16x32_bf16(a, b, c, 0, 0, 0)
; __device__ __forceinline__ void rwkv_fix_tile(const Params& p, int tile) {
;   const int mb = tile % (NSEG1 / 64), dbh = tile / (NSEG1 / 64), h = dbh & 3, b = (dbh >> 2) & 3, d = dbh >> 4;
;   const int tid = launder(threadIdx.x), lane = tid & 63, w = tid >> 6, fr = lane & 15, fq = lane >> 4;
;   const size_t rowbase = (size_t)b * TPB;
;   const int s0 = mb * 64 + 16 * w;
;   const bf16_t* gp = p.GID + ((size_t)(d * 4 + b) * NSEG1 + s0 + fr) * 256 + h * 64 + fq * 8;
;   const bf16x8 a0 = *(const bf16x8*)gp, a1 = *(const bf16x8*)(gp + 32);
; #pragma unroll
;   for (int nt = 0; nt < 4; ++nt) {
;     const float* sp = p.SMID + ((size_t)(dbh * 64 + nt * 16 + fr)) * 64 + fq * 8;
;     const float4 f0 = *(const float4*)sp, f1 = *(const float4*)(sp + 4), f2 = *(const float4*)(sp + 32), f3 = *(const float4*)(sp + 36);
;     union { unsigned u[4]; bf16x8 v; } b0, b1;
;     b0.u[0] = pack2(f0.x, f0.y); b0.u[1] = pack2(f0.z, f0.w); b0.u[2] = pack2(f1.x, f1.y); b0.u[3] = pack2(f1.z, f1.w);
;     b1.u[0] = pack2(f2.x, f2.y); b1.u[1] = pack2(f2.z, f2.w); b1.u[2] = pack2(f3.x, f3.y); b1.u[3] = pack2(f3.z, f3.w);
;     f32x4 acc = (f32x4){0.f, 0.f, 0.f, 0.f};
;     acc = MFMA(a0, b0.v, acc);
;     acc = MFMA(a1, b1.v, acc);
; #pragma unroll
;     for (int j = 0; j < 4; ++j) {
;       const int st = CSPLIT * 32 + s0 + fq * 4 + j;
;       const int pp = (d == 0) ? st : ((st < 256) ? 255 - st : 4607 - st);
;       bf16_t* yp = p.yR + ((size_t)d * TOK + rowbase + pp) * 256 + h * 64 + nt * 16 + fr;
;       *yp = f2bf(bf2f(*yp) + acc[j]);
.LBB0_123:
	s_mul_i32 s28, s46, 0xaaab
	v_mov_b32_e32 v0, v189
	s_lshr_b32 s44, s28, 20
	s_mul_i32 s28, s44, 24
	v_and_b32_e32 v12, 15, v0
	v_bfe_u32 v13, v0, 4, 2
	v_ashrrev_i32_e32 v0, 2, v0
	s_sub_i32 s28, s46, s28
	s_ashr_i32 s45, s44, 4
	v_and_b32_e32 v0, -16, v0
	s_bfe_u32 s42, s44, 0x20002
	v_lshl_add_u32 v8, s28, 6, v0
	s_lshl_b32 s28, s45, 2
	s_or_b32 s28, s28, s42
	v_ashrrev_i32_e32 v9, 31, v8
	s_mul_i32 s47, s42, 0x1100
	v_mad_i64_i32 v[0:1], s[42:43], s28, v202, v[8:9]
	v_or_b32_e32 v0, v0, v12
	v_lshlrev_b64 v[0:1], 9, v[0:1]
	s_lshl_b32 s28, s44, 7
	v_lshl_or_b32 v16, s44, 6, v12
	v_lshl_add_u64 v[0:1], s[10:11], 0, v[0:1]
	s_and_b32 s28, s28, 0x180
	v_lshlrev_b32_e32 v10, 5, v13
	v_mov_b32_e32 v11, v164
	v_ashrrev_i32_e32 v17, 31, v16
	v_lshl_add_u64 v[0:1], v[0:1], 0, s[28:29]
	v_lshlrev_b32_e32 v2, 4, v13
	v_mov_b32_e32 v3, v164
	v_lshl_add_u64 v[18:19], s[12:13], 0, v[10:11]
	v_lshlrev_b64 v[10:11], 8, v[16:17]
	v_lshl_add_u64 v[4:5], v[0:1], 0, v[2:3]
	s_waitcnt vmcnt(0)
	v_lshl_add_u64 v[28:29], v[18:19], 0, v[10:11]
	global_load_dwordx4 v[0:3], v[4:5], off
	s_nop 0
	global_load_dwordx4 v[4:7], v[4:5], off offset:64
	v_lshl_or_b32 v32, v13, 2, v8
	v_lshlrev_b32_e32 v8, 1, v12
	v_lshlrev_b32_e32 v34, 8, v16
	v_lshl_add_u32 v34, v13, 5, v34
	v_add_u32_e32 v35, 0x1000, v34
	v_add_u32_e32 v36, 0x2000, v34
	v_add_u32_e32 v37, 0x3000, v34
	global_load_dwordx4 v[40:43], v34, s[12:13]
	global_load_dwordx4 v[44:47], v34, s[12:13] offset:16
	global_load_dwordx4 v[48:51], v34, s[12:13] offset:128
	global_load_dwordx4 v[52:55], v34, s[12:13] offset:144
	global_load_dwordx4 v[56:59], v35, s[12:13]
	global_load_dwordx4 v[60:63], v35, s[12:13] offset:16
	global_load_dwordx4 v[64:67], v35, s[12:13] offset:128
	global_load_dwordx4 v[68:71], v35, s[12:13] offset:144
	global_load_dwordx4 v[72:75], v36, s[12:13]
	global_load_dwordx4 v[76:79], v36, s[12:13] offset:16
	global_load_dwordx4 v[80:83], v36, s[12:13] offset:128
	global_load_dwordx4 v[84:87], v36, s[12:13] offset:144
	global_load_dwordx4 v[88:91], v37, s[12:13]
	global_load_dwordx4 v[92:95], v37, s[12:13] offset:16
	global_load_dwordx4 v[96:99], v37, s[12:13] offset:128
	global_load_dwordx4 v[100:103], v37, s[12:13] offset:144
	s_cmp_lt_u32 s44, 16
	s_mulk_i32 s45, 0x4400
	s_cselect_b64 vcc, -1, 0
	s_add_u32 s44, s45, s47
	v_add_u32_e32 v33, 0xb00, v32
	v_cmp_lt_i32_e64 s[42:43], s40, v33
	s_nop 1
	v_cndmask_b32_e64 v38, v201, v203, s[42:43]
	s_add_u32 s42, s0, s28
	s_addc_u32 s43, s1, 0
	v_sub_u32_e32 v24, v38, v33
	v_cndmask_b32_e32 v24, v24, v33, vcc
	v_add_u32_e32 v24, s44, v24
	v_lshl_add_u32 v24, v24, 9, v8
	v_add_u32_e32 v39, 1, v33
	v_sub_u32_e32 v25, v38, v39
	v_cndmask_b32_e32 v25, v25, v39, vcc
	v_add_u32_e32 v25, s44, v25
	v_lshl_add_u32 v25, v25, 9, v8
	v_add_u32_e32 v39, 2, v33
	v_sub_u32_e32 v26, v38, v39
	v_cndmask_b32_e32 v26, v26, v39, vcc
	v_add_u32_e32 v26, s44, v26
	v_lshl_add_u32 v26, v26, 9, v8
	v_add_u32_e32 v39, 3, v33
	v_sub_u32_e32 v27, v38, v39
	v_cndmask_b32_e32 v27, v27, v39, vcc
	v_add_u32_e32 v27, s44, v27
	v_lshl_add_u32 v27, v27, 9, v8
	global_load_ushort v104, v24, s[42:43]
	global_load_ushort v105, v25, s[42:43]
	global_load_ushort v106, v26, s[42:43]
	global_load_ushort v107, v27, s[42:43]
	global_load_ushort v108, v24, s[42:43] offset:32
	global_load_ushort v109, v25, s[42:43] offset:32
	global_load_ushort v110, v26, s[42:43] offset:32
	global_load_ushort v111, v27, s[42:43] offset:32
	global_load_ushort v112, v24, s[42:43] offset:64
	global_load_ushort v113, v25, s[42:43] offset:64
	global_load_ushort v114, v26, s[42:43] offset:64
	global_load_ushort v115, v27, s[42:43] offset:64
	global_load_ushort v116, v24, s[42:43] offset:96
	global_load_ushort v117, v25, s[42:43] offset:96
	global_load_ushort v118, v26, s[42:43] offset:96
	global_load_ushort v119, v27, s[42:43] offset:96
	s_waitcnt vmcnt(0)
; __device__ __forceinline__ float bf2f(bf16_t v) { return __uint_as_float(((unsigned)v) << 16); }
; __device__ __forceinline__ bf16_t f2bf(float f) { return (bf16_t)(pack2(f, 0.f) & 0xffffu); }
; #define MFMA(a, b, c) __builtin_amdgcn_mfma_f32_16x16x32_bf16(a, b, c, 0, 0, 0)
; __device__ __forceinline__ void rwkv_fix_tile(const Params& p, int tile) {
;     ...
;   for (int nt = 0; nt < 4; ++nt) {
;     const float* sp = p.SMID + ((size_t)(dbh * 64 + nt * 16 + fr)) * 64 + fq * 8;
;     const float4 f0 = *(const float4*)sp, f1 = *(const float4*)(sp + 4), f2 = *(const float4*)(sp + 32), f3 = *(const float4*)(sp + 36);
;     union { unsigned u[4]; bf16x8 v; } b0, b1;
;     b0.u[0] = pack2(f0.x, f0.y); b0.u[1] = pack2(f0.z, f0.w); b0.u[2] = pack2(f1.x, f1.y); b0.u[3] = pack2(f1.z, f1.w);
;     b1.u[0] = pack2(f2.x, f2.y); b1.u[1] = pack2(f2.z, f2.w); b1.u[2] = pack2(f3.x, f3.y); b1.u[3] = pack2(f3.z, f3.w);
;     f32x4 acc = (f32x4){0.f, 0.f, 0.f, 0.f};
;     acc = MFMA(a0, b0.v, acc);
;     acc = MFMA(a1, b1.v, acc);
; #pragma unroll
;     for (int j = 0; j < 4; ++j) {
;       const int st = CSPLIT * 32 + s0 + fq * 4 + j;
;       const int pp = (d == 0) ? st : ((st < 256) ? 255 - st : 4607 - st);
;       bf16_t* yp = p.yR + ((size_t)d * TOK + rowbase + pp) * 256 + h * 64 + nt * 16 + fr;
;       *yp = f2bf(bf2f(*yp) + acc[j]);
;     }
;   }
	v_cvt_pk_bf16_f32 v40, v40, v41
	v_cvt_pk_bf16_f32 v41, v42, v43
	v_cvt_pk_bf16_f32 v42, v44, v45
	v_cvt_pk_bf16_f32 v43, v46, v47
	v_cvt_pk_bf16_f32 v48, v48, v49
	v_cvt_pk_bf16_f32 v49, v50, v51
	v_cvt_pk_bf16_f32 v50, v52, v53
	v_cvt_pk_bf16_f32 v51, v54, v55
	v_cvt_pk_bf16_f32 v56, v56, v57
	v_cvt_pk_bf16_f32 v57, v58, v59
	v_cvt_pk_bf16_f32 v58, v60, v61
	v_cvt_pk_bf16_f32 v59, v62, v63
	v_cvt_pk_bf16_f32 v64, v64, v65
	v_cvt_pk_bf16_f32 v65, v66, v67
	v_cvt_pk_bf16_f32 v66, v68, v69
	v_cvt_pk_bf16_f32 v67, v70, v71
	v_cvt_pk_bf16_f32 v72, v72, v73
	v_cvt_pk_bf16_f32 v73, v74, v75
	v_cvt_pk_bf16_f32 v74, v76, v77
	v_cvt_pk_bf16_f32 v75, v78, v79
	v_cvt_pk_bf16_f32 v80, v80, v81
	v_cvt_pk_bf16_f32 v81, v82, v83
	v_cvt_pk_bf16_f32 v82, v84, v85
	v_cvt_pk_bf16_f32 v83, v86, v87
	v_cvt_pk_bf16_f32 v88, v88, v89
	v_cvt_pk_bf16_f32 v89, v90, v91
	v_cvt_pk_bf16_f32 v90, v92, v93
	v_cvt_pk_bf16_f32 v91, v94, v95
	v_cvt_pk_bf16_f32 v96, v96, v97
	v_cvt_pk_bf16_f32 v97, v98, v99
	v_cvt_pk_bf16_f32 v98, v100, v101
	v_cvt_pk_bf16_f32 v99, v102, v103
	s_nop 1
	v_mfma_f32_16x16x32_bf16 v[120:123], v[0:3], v[40:43], 0
	v_mfma_f32_16x16x32_bf16 v[124:127], v[0:3], v[56:59], 0
	v_mfma_f32_16x16x32_bf16 v[128:131], v[0:3], v[72:75], 0
	v_mfma_f32_16x16x32_bf16 v[132:135], v[0:3], v[88:91], 0
	v_mfma_f32_16x16x32_bf16 v[120:123], v[4:7], v[48:51], v[120:123]
	v_mfma_f32_16x16x32_bf16 v[124:127], v[4:7], v[64:67], v[124:127]
	v_mfma_f32_16x16x32_bf16 v[128:131], v[4:7], v[80:83], v[128:131]
	v_mfma_f32_16x16x32_bf16 v[132:135], v[4:7], v[96:99], v[132:135]
	v_lshlrev_b32_e32 v104, 16, v104
	v_lshlrev_b32_e32 v105, 16, v105
	v_lshlrev_b32_e32 v106, 16, v106
	v_lshlrev_b32_e32 v107, 16, v107
	v_lshlrev_b32_e32 v108, 16, v108
	v_lshlrev_b32_e32 v109, 16, v109
	v_lshlrev_b32_e32 v110, 16, v110
	v_lshlrev_b32_e32 v111, 16, v111
	v_lshlrev_b32_e32 v112, 16, v112
	v_lshlrev_b32_e32 v113, 16, v113
	v_lshlrev_b32_e32 v114, 16, v114
	v_lshlrev_b32_e32 v115, 16, v115
	v_lshlrev_b32_e32 v116, 16, v116
	v_lshlrev_b32_e32 v117, 16, v117
	v_lshlrev_b32_e32 v118, 16, v118
	v_lshlrev_b32_e32 v119, 16, v119
	s_nop 7
	v_add_f32_e32 v104, v120, v104
	v_add_f32_e32 v105, v121, v105
	v_add_f32_e32 v106, v122, v106
	v_add_f32_e32 v107, v123, v107
	v_add_f32_e32 v108, v124, v108
	v_add_f32_e32 v109, v125, v109
	v_add_f32_e32 v110, v126, v110
	v_add_f32_e32 v111, v127, v111
	v_add_f32_e32 v112, v128, v112
	v_add_f32_e32 v113, v129, v113
	v_add_f32_e32 v114, v130, v114
	v_add_f32_e32 v115, v131, v115
	v_add_f32_e32 v116, v132, v116
	v_add_f32_e32 v117, v133, v117
	v_add_f32_e32 v118, v134, v118
	v_add_f32_e32 v119, v135, v119
	v_cvt_pk_bf16_f32 v104, v104, v104
	v_cvt_pk_bf16_f32 v105, v105, v105
	v_cvt_pk_bf16_f32 v106, v106, v106
	v_cvt_pk_bf16_f32 v107, v107, v107
	v_cvt_pk_bf16_f32 v108, v108, v108
	v_cvt_pk_bf16_f32 v109, v109, v109
	v_cvt_pk_bf16_f32 v110, v110, v110
	v_cvt_pk_bf16_f32 v111, v111, v111
	v_cvt_pk_bf16_f32 v112, v112, v112
	v_cvt_pk_bf16_f32 v113, v113, v113
	v_cvt_pk_bf16_f32 v114, v114, v114
	v_cvt_pk_bf16_f32 v115, v115, v115
	v_cvt_pk_bf16_f32 v116, v116, v116
	v_cvt_pk_bf16_f32 v117, v117, v117
	v_cvt_pk_bf16_f32 v118, v118, v118
	v_cvt_pk_bf16_f32 v119, v119, v119
	global_store_short v24, v104, s[42:43]
	global_store_short v25, v105, s[42:43]
	global_store_short v26, v106, s[42:43]
	global_store_short v27, v107, s[42:43]
	global_store_short v24, v108, s[42:43] offset:32
	global_store_short v25, v109, s[42:43] offset:32
	global_store_short v26, v110, s[42:43] offset:32
	global_store_short v27, v111, s[42:43] offset:32
	global_store_short v24, v112, s[42:43] offset:64
	global_store_short v25, v113, s[42:43] offset:64
	global_store_short v26, v114, s[42:43] offset:64
	global_store_short v27, v115, s[42:43] offset:64
	global_store_short v24, v116, s[42:43] offset:96
	global_store_short v25, v117, s[42:43] offset:96
	global_store_short v26, v118, s[42:43] offset:96
	global_store_short v27, v119, s[42:43] offset:96
	s_load_dword s28, s[2:3], 0x0
	s_waitcnt lgkmcnt(0)
	s_add_i32 s46, s28, s46
	s_cmpk_gt_i32 s46, 0x2ff
	s_cbranch_scc0 .LBB0_123

; __device__ __forceinline__ int launder(int x) { asm volatile("" : "+v"(x)); return x; }
; __device__ __forceinline__ void ssd_conv_tile(const Params& p, int l, int tile, unsigned char* smem) {
;   const int b = tile >> 7, t34 = tile & 127, pp0 = t34 * 34;
;   const size_t r0 = (size_t)b * TPB + pp0;
;   bf16_t* T = (bf16_t*)smem;
;   const int tid = launder(threadIdx.x);
;   for (int q = tid; q < 34 * 112; q += 256) {
;     const int rr = q / 112, cc = q % 112;
;     *(uint4*)(T + (rr + 1) * 896 + cc * 8) = *(const uint4*)(p.PS + (r0 + rr) * 912 + cc * 8);
;   }
.LBB0_802:
	s_and_b64 vcc, exec, s[42:43]
	s_cbranch_vccz .LBB0_830
	s_add_i32 s61, s47, 0xfffffbc0
	s_lshr_b32 s28, s61, 7
	s_and_b32 s58, s61, 0x7f
	s_mul_i32 s60, s58, 34
	s_mulk_i32 s28, 0x1100
	s_waitcnt vmcnt(0)
	v_mov_b32_e32 v33, v189
	s_movk_i32 s42, 0xee0
	s_add_i32 s28, s28, s60
	s_nop 0
	v_cmp_gt_i32_e32 vcc, s42, v33
	s_and_saveexec_b64 s[42:43], vcc
	v_readlane_b32 s0, v251, 48
	v_readlane_b32 s14, v251, 62
	v_readlane_b32 s15, v251, 63
	s_mov_b32 s0, 0x92492493
	v_readlane_b32 s1, v251, 49
	v_readlane_b32 s2, v251, 50
	v_readlane_b32 s3, v251, 51
	v_readlane_b32 s4, v251, 52
	v_readlane_b32 s5, v251, 53
	v_readlane_b32 s6, v251, 54
	v_readlane_b32 s7, v251, 55
	v_readlane_b32 s8, v251, 56
	v_readlane_b32 s9, v251, 57
	v_readlane_b32 s10, v251, 58
	v_readlane_b32 s11, v251, 59
	v_readlane_b32 s12, v251, 60
	v_readlane_b32 s13, v251, 61
	s_cbranch_execz .LBB0_806
	v_readlane_b32 s4, v255, 29
	s_mov_b32 s1, 0x2492493
	s_movk_i32 s2, 0x720
	s_movk_i32 s3, 0xe0
	v_lshl_add_u32 v124, v33, 4, s4
	v_mul_hi_u32 v121, v33, s1
	v_mul_u32_u24_e32 v122, 0x70, v121
	v_sub_u32_e32 v122, v33, v122
	v_add_u32_e32 v121, s28, v121
	v_mul_u32_u24_e32 v121, s2, v121
	v_lshl_add_u32 v121, v122, 4, v121
	global_load_dwordx4 v[60:63], v121, s[14:15]
	v_add_u32_e32 v120, 0x100, v33
	v_mul_hi_u32 v121, v120, s1
	v_mul_u32_u24_e32 v122, 0x70, v121
	v_sub_u32_e32 v122, v120, v122
	v_add_u32_e32 v121, s28, v121
	v_mul_u32_u24_e32 v121, s2, v121
	v_lshl_add_u32 v121, v122, 4, v121
	global_load_dwordx4 v[64:67], v121, s[14:15]
	v_add_u32_e32 v120, 0x200, v33
	v_mul_hi_u32 v121, v120, s1
	v_mul_u32_u24_e32 v122, 0x70, v121
	v_sub_u32_e32 v122, v120, v122
	v_add_u32_e32 v121, s28, v121
	v_mul_u32_u24_e32 v121, s2, v121
	v_lshl_add_u32 v121, v122, 4, v121
	global_load_dwordx4 v[68:71], v121, s[14:15]
	v_add_u32_e32 v120, 0x300, v33
	v_mul_hi_u32 v121, v120, s1
	v_mul_u32_u24_e32 v122, 0x70, v121
	v_sub_u32_e32 v122, v120, v122
	v_add_u32_e32 v121, s28, v121
	v_mul_u32_u24_e32 v121, s2, v121
	v_lshl_add_u32 v121, v122, 4, v121
	global_load_dwordx4 v[72:75], v121, s[14:15]
	v_add_u32_e32 v120, 0x400, v33
	v_mul_hi_u32 v121, v120, s1
	v_mul_u32_u24_e32 v122, 0x70, v121
	v_sub_u32_e32 v122, v120, v122
	v_add_u32_e32 v121, s28, v121
	v_mul_u32_u24_e32 v121, s2, v121
	v_lshl_add_u32 v121, v122, 4, v121
	global_load_dwordx4 v[76:79], v121, s[14:15]
	v_add_u32_e32 v120, 0x500, v33
	v_mul_hi_u32 v121, v120, s1
	v_mul_u32_u24_e32 v122, 0x70, v121
	v_sub_u32_e32 v122, v120, v122
	v_add_u32_e32 v121, s28, v121
	v_mul_u32_u24_e32 v121, s2, v121
	v_lshl_add_u32 v121, v122, 4, v121
	global_load_dwordx4 v[80:83], v121, s[14:15]
	v_add_u32_e32 v120, 0x600, v33
	v_mul_hi_u32 v121, v120, s1
	v_mul_u32_u24_e32 v122, 0x70, v121
	v_sub_u32_e32 v122, v120, v122
	v_add_u32_e32 v121, s28, v121
	v_mul_u32_u24_e32 v121, s2, v121
	v_lshl_add_u32 v121, v122, 4, v121
	global_load_dwordx4 v[84:87], v121, s[14:15]
	v_add_u32_e32 v120, 0x700, v33
	v_mul_hi_u32 v121, v120, s1
	v_mul_u32_u24_e32 v122, 0x70, v121
	v_sub_u32_e32 v122, v120, v122
	v_add_u32_e32 v121, s28, v121
	v_mul_u32_u24_e32 v121, s2, v121
	v_lshl_add_u32 v121, v122, 4, v121
	global_load_dwordx4 v[88:91], v121, s[14:15]
	v_add_u32_e32 v120, 0x800, v33
	v_mul_hi_u32 v121, v120, s1
	v_mul_u32_u24_e32 v122, 0x70, v121
	v_sub_u32_e32 v122, v120, v122
	v_add_u32_e32 v121, s28, v121
	v_mul_u32_u24_e32 v121, s2, v121
	v_lshl_add_u32 v121, v122, 4, v121
	global_load_dwordx4 v[92:95], v121, s[14:15]
	v_add_u32_e32 v120, 0x900, v33
	v_mul_hi_u32 v121, v120, s1
	v_mul_u32_u24_e32 v122, 0x70, v121
	v_sub_u32_e32 v122, v120, v122
	v_add_u32_e32 v121, s28, v121
	v_mul_u32_u24_e32 v121, s2, v121
	v_lshl_add_u32 v121, v122, 4, v121
	global_load_dwordx4 v[96:99], v121, s[14:15]
	v_add_u32_e32 v120, 0xa00, v33
	v_mul_hi_u32 v121, v120, s1
	v_mul_u32_u24_e32 v122, 0x70, v121
	v_sub_u32_e32 v122, v120, v122
	v_add_u32_e32 v121, s28, v121
	v_mul_u32_u24_e32 v121, s2, v121
	v_lshl_add_u32 v121, v122, 4, v121
	global_load_dwordx4 v[100:103], v121, s[14:15]
	v_add_u32_e32 v120, 0xb00, v33
	v_mul_hi_u32 v121, v120, s1
	v_mul_u32_u24_e32 v122, 0x70, v121
	v_sub_u32_e32 v122, v120, v122
	v_add_u32_e32 v121, s28, v121
	v_mul_u32_u24_e32 v121, s2, v121
	v_lshl_add_u32 v121, v122, 4, v121
	global_load_dwordx4 v[104:107], v121, s[14:15]
	v_add_u32_e32 v120, 0xc00, v33
	v_mul_hi_u32 v121, v120, s1
	v_mul_u32_u24_e32 v122, 0x70, v121
	v_sub_u32_e32 v122, v120, v122
	v_add_u32_e32 v121, s28, v121
	v_mul_u32_u24_e32 v121, s2, v121
	v_lshl_add_u32 v121, v122, 4, v121
	global_load_dwordx4 v[108:111], v121, s[14:15]
	v_add_u32_e32 v120, 0xd00, v33
	v_mul_hi_u32 v121, v120, s1
	v_mul_u32_u24_e32 v122, 0x70, v121
	v_sub_u32_e32 v122, v120, v122
	v_add_u32_e32 v121, s28, v121
	v_mul_u32_u24_e32 v121, s2, v121
	v_lshl_add_u32 v121, v122, 4, v121
	global_load_dwordx4 v[112:115], v121, s[14:15]
	v_add_u32_e32 v120, 0xe00, v33
	v_mul_hi_u32 v121, v120, s1
	v_mul_u32_u24_e32 v122, 0x70, v121
	v_sub_u32_e32 v122, v120, v122
	v_add_u32_e32 v121, s28, v121
	v_mul_u32_u24_e32 v121, s2, v121
	v_lshl_add_u32 v121, v122, 4, v121
	v_cmp_gt_u32_e64 s[44:45], s3, v33
	s_and_saveexec_b64 s[56:57], s[44:45]
	global_load_dwordx4 v[116:119], v121, s[14:15]
	s_mov_b64 exec, s[56:57]

; __device__ __forceinline__ void ssd_conv_tile(const Params& p, int l, int tile, unsigned char* smem) {
;     ...
;   for (int q = tid; q < 34 * 112; q += 256) {
;     const int rr = q / 112, cc = q % 112;
;     *(uint4*)(T + (rr + 1) * 896 + cc * 8) = *(const uint4*)(p.PS + (r0 + rr) * 912 + cc * 8);
;   }
;   if (tid < 224) {
;     const int which = tid / 112, cc = tid % 112;
;     const bool ex = (which == 0) ? (t34 >= 1) : (t34 + 1 < 128);
;     uint4 v = make_uint4(0, 0, 0, 0);
;     if (ex) v = *(const uint4*)(p.HALO + ((size_t)(b * 128 + t34) * 2 + which) * 896 + cc * 8);
;     *(uint4*)(T + (which ? 35 : 0) * 896 + cc * 8) = v;
;   }
;   __syncthreads();
;   const float* cw = p.ssm_conv_w + (size_t)l * 3 * 896;
;   const float* cb = p.ssm_conv_b + (size_t)l * 896;
;   if (tid < 224) {
;     const int g8 = tid % 112, rpar = tid / 112, c0 = g8 * 8;
;     float w0[8], w1[8], w2[8], bs[8];
; #pragma unroll
;     for (int e = 0; e < 8; ++e) { w0[e] = cw[c0 + e]; w1[e] = cw[896 + c0 + e]; w2[e] = cw[1792 + c0 + e]; bs[e] = cb[c0 + e]; }
.LBB0_810:
	s_or_b64 exec, exec, s[56:57]
	s_waitcnt vmcnt(0)
	ds_write_b128 v124, v[60:63]
	ds_write_b128 v124, v[64:67] offset:4096
	ds_write_b128 v124, v[68:71] offset:8192
	ds_write_b128 v124, v[72:75] offset:12288
	ds_write_b128 v124, v[76:79] offset:16384
	ds_write_b128 v124, v[80:83] offset:20480
	ds_write_b128 v124, v[84:87] offset:24576
	ds_write_b128 v124, v[88:91] offset:28672
	ds_write_b128 v124, v[92:95] offset:32768
	ds_write_b128 v124, v[96:99] offset:36864
	ds_write_b128 v124, v[100:103] offset:40960
	ds_write_b128 v124, v[104:107] offset:45056
	ds_write_b128 v124, v[108:111] offset:49152
	ds_write_b128 v124, v[112:115] offset:53248
	s_and_saveexec_b64 s[44:45], vcc
	ds_write_b128 v124, v[116:119] offset:57344
	s_mov_b64 exec, s[44:45]
	s_waitcnt lgkmcnt(0)
	s_barrier
	s_and_saveexec_b64 s[42:43], vcc
	s_cbranch_execz .LBB0_813
	v_lshrrev_b32_e32 v0, 31, v6
	v_ashrrev_i32_e32 v1, 6, v6
	v_add_u32_e32 v32, v1, v0
	s_movk_i32 s0, 0x70
	v_mul_lo_u32 v0, v32, s0
	v_sub_u32_e32 v0, v33, v0
	v_lshlrev_b32_e32 v34, 3, v0
	v_ashrrev_i32_e32 v35, 31, v34
	v_lshlrev_b64 v[0:1], 2, v[34:35]
	v_lshl_add_u64 v[16:17], s[50:51], 0, v[0:1]
	s_mov_b64 s[44:45], 0x1c00
	v_lshl_add_u64 v[20:21], v[16:17], 0, s[44:45]
	v_lshl_add_u64 v[28:29], s[48:49], 0, v[0:1]
	global_load_dwordx4 v[0:3], v[16:17], off offset:16
	global_load_dwordx4 v[4:7], v[16:17], off
	global_load_dwordx4 v[8:11], v[16:17], off offset:3600
	global_load_dwordx4 v[12:15], v[16:17], off offset:3584
	v_add_co_u32_e32 v16, vcc, s31, v16
	v_lshl_add_u32 v37, v33, 4, 0
	s_nop 0
	v_addc_co_u32_e32 v17, vcc, 0, v17, vcc
	global_load_dwordx4 v[16:19], v[16:17], off offset:3072
	s_nop 0
	global_load_dwordx4 v[20:23], v[20:21], off offset:16
	s_nop 0
	global_load_dwordx4 v[24:27], v[28:29], off offset:16
	s_nop 0
	global_load_dwordx4 v[28:31], v[28:29], off
	v_ashrrev_i32_e32 v33, 31, v32
	v_lshl_add_u64 v[38:39], v[32:33], 0, s[28:29]
	v_lshlrev_b64 v[34:35], 1, v[34:35]
	v_mad_u64_u32 v[34:35], s[44:45], v38, s39, v[34:35]
	v_readlane_b32 s0, v251, 48
	v_mad_i32_i24 v35, v39, s39, v35
	v_readlane_b32 s14, v251, 62
	v_readlane_b32 s15, v251, 63
	s_mov_b64 s[44:45], 0
	v_readlane_b32 s1, v251, 49
	v_lshl_add_u64 v[34:35], s[14:15], 0, v[34:35]
	v_readlane_b32 s2, v251, 50
	v_readlane_b32 s3, v251, 51
	v_readlane_b32 s4, v251, 52
	v_readlane_b32 s5, v251, 53
	v_readlane_b32 s6, v251, 54
	v_readlane_b32 s7, v251, 55
	v_readlane_b32 s8, v251, 56
	v_readlane_b32 s9, v251, 57
	v_readlane_b32 s10, v251, 58
	v_readlane_b32 s11, v251, 59
	v_readlane_b32 s12, v251, 60
	v_readlane_b32 s13, v251, 61
	s_waitcnt vmcnt(0)

; template <bool DUAL>
; __device__ __forceinline__ void rwkv_tile(const Params& p, int l, int tile, unsigned char* smem) {
;     ...
; #pragma unroll 2
;       for (int i = 0; i < 32; ++i) {
;         const int inx = (i + 1) & 31;
;         const float4 nw4 = *(const float4*)(rp + inx * 384), nkk4 = *(const float4*)(rp + inx * 384 + 64), nkb4 = *(const float4*)(rp + inx * 384 + 128);
;         const float4 nkd4 = *(const float4*)(rp + inx * 384 + 192), nr4 = *(const float4*)(rp + inx * 384 + 256);
;         const float nv = vp[inx * 384];
;         v2f t = sA * (v2f){kk4.x, kk4.y};
;         t = sB * (v2f){kk4.z, kk4.w} + t;
;         float sa = t.x + t.y, ia = 0.f;
;         if (DUAL) {
;           v2f ti = iA * (v2f){kk4.x, kk4.y};
;           ti = iB * (v2f){kk4.z, kk4.w} + ti;
;           ia = ti.x + ti.y;
;           sa += dppf<0xB1>(sa); ia += dppf<0xB1>(ia);
;           sa += dppf<0x4E>(sa); ia += dppf<0x4E>(ia);
;           sa += dppf<0x141>(sa); ia += dppf<0x141>(ia);
;           sa += dppf<0x140>(sa); ia += dppf<0x140>(ia);
;         } else {
;           sa = sum16(sa);
;         }
;         v2f cA = sA * (v2f){w4.x, w4.y} + (v2f){kd4.x, kd4.y} * v;
;         v2f cB = sB * (v2f){w4.z, w4.w} + (v2f){kd4.z, kd4.w} * v;
;         sA = cA - (v2f){kb4.x, kb4.y} * sa;
;         sB = cB - (v2f){kb4.z, kb4.w} * sa;
;         v2f u = sA * (v2f){r4.x, r4.y};
;         u = sB * (v2f){r4.z, r4.w} + u;
;         float y = u.x + u.y, g = 0.f;
;         if (DUAL) {
;           iA = iA * (v2f){w4.x, w4.y} - (v2f){kb4.x, kb4.y} * ia;
;           iB = iB * (v2f){w4.z, w4.w} - (v2f){kb4.z, kb4.w} * ia;
;           v2f ui = iA * (v2f){r4.x, r4.y};
;           ui = iB * (v2f){r4.z, r4.w} + ui;
;           g = ui.x + ui.y;
;           y += dppf<0xB1>(y); g += dppf<0xB1>(g);
;           y += dppf<0x4E>(y); g += dppf<0x4E>(g);
;           y += dppf<0x141>(y); g += dppf<0x141>(g);
;           y += dppf<0x140>(y); g += dppf<0x140>(g);
;           if (fr == (i & 15)) gkeep = g;
;         } else {
;           y = sum16(y);
;         }
;         if (fr == (i & 15)) ykeep = y;
;         if ((i & 15) == 15) {
;           const int ii = (i & 16) + fr;
;           const int ri = (d == 0) ? ii + 1 : 32 - ii;
;           const int pi = plo - 1 + ri;
;           p.yR[((size_t)d * TOK + rowbase + pi) * 256 + h * 64 + row] = f2bf(ykeep);
.Lrw_du_scan:
	v_mov_b32_e32 v74, v102
	v_mov_b32_e32 v75, v103
	v_add_u32_e32 v69, 0x6000, v102
	v_add_u32_e32 v70, 0x6000, v103
	v_mov_b32_e32 v68, v101
	s_mov_b32 vcc_lo, 0xcccccccc
	s_mov_b32 vcc_hi, 0xcccccccc
	s_mov_b32 s58, 0xaaaaaaaa
	s_mov_b32 s59, 0xaaaaaaaa
	ds_read_b128 v[220:223], v74 offset:25600
	ds_read_b128 v[216:219], v74 offset:25344
	ds_read_b128 v[228:231], v74 offset:26112
	ds_read_b32 v236, v75 offset:26624
	ds_read_b128 v[224:227], v74 offset:25856
	ds_read_b128 v[232:235], v74 offset:26368
	ds_read_b128 v[126:129], v74 offset:27136
	ds_read_b128 v[122:125], v74 offset:26880
	ds_read_b128 v[134:137], v74 offset:27648
	ds_read_b32 v142, v75 offset:28160
	ds_read_b128 v[130:133], v74 offset:27392
	ds_read_b128 v[138:141], v74 offset:27904
	s_mov_b32 s55, 0
.Lrw_du_loop:
	s_waitcnt lgkmcnt(6)
	v_pk_mul_f32 v[60:61], v[94:95], v[220:221]
	v_pk_mul_f32 v[62:63], v[88:89], v[220:221]
	v_pk_fma_f32 v[60:61], v[92:93], v[222:223], v[60:61]
	v_pk_fma_f32 v[62:63], v[90:91], v[222:223], v[62:63]
	v_add_f32_e32 v60, v60, v61
	v_add_f32_e32 v62, v62, v63
	v_pk_mul_f32 v[94:95], v[94:95], v[216:217]
	v_pk_mul_f32 v[92:93], v[92:93], v[218:219]
	v_add_f32_dpp v60, v60, v60 quad_perm:[1,0,3,2] row_mask:0xf bank_mask:0xf bound_ctrl:1
	v_add_f32_dpp v62, v62, v62 quad_perm:[1,0,3,2] row_mask:0xf bank_mask:0xf bound_ctrl:1
	v_pk_fma_f32 v[94:95], v[236:237], v[228:229], v[94:95] op_sel_hi:[0,1,1]
	v_add_f32_dpp v60, v60, v60 quad_perm:[2,3,0,1] row_mask:0xf bank_mask:0xf bound_ctrl:1
	v_add_f32_dpp v62, v62, v62 quad_perm:[2,3,0,1] row_mask:0xf bank_mask:0xf bound_ctrl:1
	v_pk_fma_f32 v[92:93], v[236:237], v[230:231], v[92:93] op_sel_hi:[0,1,1]
	v_add_f32_dpp v60, v60, v60 row_half_mirror row_mask:0xf bank_mask:0xf bound_ctrl:1
	v_add_f32_dpp v62, v62, v62 row_half_mirror row_mask:0xf bank_mask:0xf bound_ctrl:1
	ds_read_b128 v[220:223], v74 offset:28672
	v_add_f32_dpp v60, v60, v60 row_mirror row_mask:0xf bank_mask:0xf bound_ctrl:1
	v_add_f32_dpp v62, v62, v62 row_mirror row_mask:0xf bank_mask:0xf bound_ctrl:1
	ds_read_b128 v[228:231], v74 offset:29184
	ds_read_b32 v236, v75 offset:29696
	v_pk_fma_f32 v[94:95], v[224:225], v[60:61], v[94:95] op_sel_hi:[1,0,1] neg_lo:[1,0,0] neg_hi:[1,0,0]
	v_pk_fma_f32 v[92:93], v[226:227], v[60:61], v[92:93] op_sel_hi:[1,0,1] neg_lo:[1,0,0] neg_hi:[1,0,0]
	v_pk_mul_f32 v[238:239], v[224:225], v[62:63] op_sel_hi:[1,0]
	v_pk_mul_f32 v[240:241], v[226:227], v[62:63] op_sel_hi:[1,0]
	ds_read_b128 v[224:227], v74 offset:28928
	v_pk_mul_f32 v[64:65], v[232:233], v[94:95]
	v_pk_fma_f32 v[88:89], v[88:89], v[216:217], v[238:239] neg_lo:[0,0,1] neg_hi:[0,0,1]
	v_pk_fma_f32 v[90:91], v[90:91], v[218:219], v[240:241] neg_lo:[0,0,1] neg_hi:[0,0,1]
	ds_read_b128 v[216:219], v74 offset:28416
	v_pk_fma_f32 v[64:65], v[234:235], v[92:93], v[64:65]
	v_pk_mul_f32 v[66:67], v[232:233], v[88:89]
	v_pk_fma_f32 v[66:67], v[234:235], v[90:91], v[66:67]
	ds_read_b128 v[232:235], v74 offset:29440
	v_add_f32_e32 v144, v64, v65
	v_add_f32_e32 v165, v66, v67
	s_waitcnt lgkmcnt(6)
	v_pk_mul_f32 v[60:61], v[94:95], v[126:127]
	v_pk_mul_f32 v[62:63], v[88:89], v[126:127]
	v_pk_fma_f32 v[60:61], v[92:93], v[128:129], v[60:61]
	v_pk_fma_f32 v[62:63], v[90:91], v[128:129], v[62:63]
	v_add_f32_e32 v60, v60, v61
	v_add_f32_e32 v62, v62, v63
	v_pk_mul_f32 v[94:95], v[94:95], v[122:123]
	v_pk_mul_f32 v[92:93], v[92:93], v[124:125]
	v_add_f32_dpp v60, v60, v60 quad_perm:[1,0,3,2] row_mask:0xf bank_mask:0xf bound_ctrl:1
	v_add_f32_dpp v62, v62, v62 quad_perm:[1,0,3,2] row_mask:0xf bank_mask:0xf bound_ctrl:1
	v_pk_fma_f32 v[94:95], v[142:143], v[134:135], v[94:95] op_sel_hi:[0,1,1]
	v_add_f32_dpp v60, v60, v60 quad_perm:[2,3,0,1] row_mask:0xf bank_mask:0xf bound_ctrl:1
	v_add_f32_dpp v62, v62, v62 quad_perm:[2,3,0,1] row_mask:0xf bank_mask:0xf bound_ctrl:1
	v_pk_fma_f32 v[92:93], v[142:143], v[136:137], v[92:93] op_sel_hi:[0,1,1]
	v_add_f32_dpp v60, v60, v60 row_half_mirror row_mask:0xf bank_mask:0xf bound_ctrl:1
	v_add_f32_dpp v62, v62, v62 row_half_mirror row_mask:0xf bank_mask:0xf bound_ctrl:1
	ds_read_b128 v[126:129], v74 offset:30208
	v_add_f32_dpp v60, v60, v60 row_mirror row_mask:0xf bank_mask:0xf bound_ctrl:1
	v_add_f32_dpp v62, v62, v62 row_mirror row_mask:0xf bank_mask:0xf bound_ctrl:1
	ds_read_b128 v[134:137], v74 offset:30720
	ds_read_b32 v142, v75 offset:31232
	v_pk_fma_f32 v[94:95], v[130:131], v[60:61], v[94:95] op_sel_hi:[1,0,1] neg_lo:[1,0,0] neg_hi:[1,0,0]
	v_pk_fma_f32 v[92:93], v[132:133], v[60:61], v[92:93] op_sel_hi:[1,0,1] neg_lo:[1,0,0] neg_hi:[1,0,0]
	v_pk_mul_f32 v[238:239], v[130:131], v[62:63] op_sel_hi:[1,0]
	v_pk_mul_f32 v[240:241], v[132:133], v[62:63] op_sel_hi:[1,0]
	ds_read_b128 v[130:133], v74 offset:30464
	v_pk_mul_f32 v[64:65], v[138:139], v[94:95]
	v_pk_fma_f32 v[88:89], v[88:89], v[122:123], v[238:239] neg_lo:[0,0,1] neg_hi:[0,0,1]
	v_pk_fma_f32 v[90:91], v[90:91], v[124:125], v[240:241] neg_lo:[0,0,1] neg_hi:[0,0,1]
	ds_read_b128 v[122:125], v74 offset:29952
	v_pk_fma_f32 v[64:65], v[140:141], v[92:93], v[64:65]
	v_pk_mul_f32 v[66:67], v[138:139], v[88:89]
	v_pk_fma_f32 v[66:67], v[140:141], v[90:91], v[66:67]
	ds_read_b128 v[138:141], v74 offset:30976
	v_add_f32_e32 v145, v64, v65
	v_add_f32_e32 v166, v66, v67
	s_waitcnt lgkmcnt(6)
; template <bool DUAL>
; __device__ __forceinline__ void rwkv_tile(const Params& p, int l, int tile, unsigned char* smem) {
;     ...
; #pragma unroll 2
;       for (int i = 0; i < 32; ++i) {
;         const int inx = (i + 1) & 31;
;         const float4 nw4 = *(const float4*)(rp + inx * 384), nkk4 = *(const float4*)(rp + inx * 384 + 64), nkb4 = *(const float4*)(rp + inx * 384 + 128);
;         const float4 nkd4 = *(const float4*)(rp + inx * 384 + 192), nr4 = *(const float4*)(rp + inx * 384 + 256);
;         const float nv = vp[inx * 384];
;         v2f t = sA * (v2f){kk4.x, kk4.y};
;         t = sB * (v2f){kk4.z, kk4.w} + t;
;         float sa = t.x + t.y, ia = 0.f;
;         if (DUAL) {
;           v2f ti = iA * (v2f){kk4.x, kk4.y};
;           ti = iB * (v2f){kk4.z, kk4.w} + ti;
;           ia = ti.x + ti.y;
;           sa += dppf<0xB1>(sa); ia += dppf<0xB1>(ia);
;           sa += dppf<0x4E>(sa); ia += dppf<0x4E>(ia);
;           sa += dppf<0x141>(sa); ia += dppf<0x141>(ia);
;           sa += dppf<0x140>(sa); ia += dppf<0x140>(ia);
;         } else {
;           sa = sum16(sa);
;         }
;         v2f cA = sA * (v2f){w4.x, w4.y} + (v2f){kd4.x, kd4.y} * v;
;         v2f cB = sB * (v2f){w4.z, w4.w} + (v2f){kd4.z, kd4.w} * v;
;         sA = cA - (v2f){kb4.x, kb4.y} * sa;
;         sB = cB - (v2f){kb4.z, kb4.w} * sa;
;         v2f u = sA * (v2f){r4.x, r4.y};
;         u = sB * (v2f){r4.z, r4.w} + u;
;         float y = u.x + u.y, g = 0.f;
;         if (DUAL) {
;           iA = iA * (v2f){w4.x, w4.y} - (v2f){kb4.x, kb4.y} * ia;
;           iB = iB * (v2f){w4.z, w4.w} - (v2f){kb4.z, kb4.w} * ia;
;           v2f ui = iA * (v2f){r4.x, r4.y};
;           ui = iB * (v2f){r4.z, r4.w} + ui;
;           g = ui.x + ui.y;
;           y += dppf<0xB1>(y); g += dppf<0xB1>(g);
;           y += dppf<0x4E>(y); g += dppf<0x4E>(g);
;           y += dppf<0x141>(y); g += dppf<0x141>(g);
;           y += dppf<0x140>(y); g += dppf<0x140>(g);
;           if (fr == (i & 15)) gkeep = g;
;         } else {
;           y = sum16(y);
;         }
;         if (fr == (i & 15)) ykeep = y;
	v_pk_mul_f32 v[60:61], v[94:95], v[220:221]
	v_pk_mul_f32 v[62:63], v[88:89], v[220:221]
	v_pk_fma_f32 v[60:61], v[92:93], v[222:223], v[60:61]
	v_pk_fma_f32 v[62:63], v[90:91], v[222:223], v[62:63]
	v_add_f32_e32 v60, v60, v61
	v_add_f32_e32 v62, v62, v63
	v_pk_mul_f32 v[94:95], v[94:95], v[216:217]
	v_pk_mul_f32 v[92:93], v[92:93], v[218:219]
	v_add_f32_dpp v60, v60, v60 quad_perm:[1,0,3,2] row_mask:0xf bank_mask:0xf bound_ctrl:1
	v_add_f32_dpp v62, v62, v62 quad_perm:[1,0,3,2] row_mask:0xf bank_mask:0xf bound_ctrl:1
	v_pk_fma_f32 v[94:95], v[236:237], v[228:229], v[94:95] op_sel_hi:[0,1,1]
	v_add_f32_dpp v60, v60, v60 quad_perm:[2,3,0,1] row_mask:0xf bank_mask:0xf bound_ctrl:1
	v_add_f32_dpp v62, v62, v62 quad_perm:[2,3,0,1] row_mask:0xf bank_mask:0xf bound_ctrl:1
	v_pk_fma_f32 v[92:93], v[236:237], v[230:231], v[92:93] op_sel_hi:[0,1,1]
	v_add_f32_dpp v60, v60, v60 row_half_mirror row_mask:0xf bank_mask:0xf bound_ctrl:1
	v_add_f32_dpp v62, v62, v62 row_half_mirror row_mask:0xf bank_mask:0xf bound_ctrl:1
	ds_read_b128 v[220:223], v74 offset:31744
	v_add_f32_dpp v60, v60, v60 row_mirror row_mask:0xf bank_mask:0xf bound_ctrl:1
	v_add_f32_dpp v62, v62, v62 row_mirror row_mask:0xf bank_mask:0xf bound_ctrl:1
	ds_read_b128 v[228:231], v74 offset:32256
	ds_read_b32 v236, v75 offset:32768
	v_pk_fma_f32 v[94:95], v[224:225], v[60:61], v[94:95] op_sel_hi:[1,0,1] neg_lo:[1,0,0] neg_hi:[1,0,0]
	v_pk_fma_f32 v[92:93], v[226:227], v[60:61], v[92:93] op_sel_hi:[1,0,1] neg_lo:[1,0,0] neg_hi:[1,0,0]
	v_pk_mul_f32 v[238:239], v[224:225], v[62:63] op_sel_hi:[1,0]
	v_pk_mul_f32 v[240:241], v[226:227], v[62:63] op_sel_hi:[1,0]
	ds_read_b128 v[224:227], v74 offset:32000
	v_pk_mul_f32 v[64:65], v[232:233], v[94:95]
	v_pk_fma_f32 v[88:89], v[88:89], v[216:217], v[238:239] neg_lo:[0,0,1] neg_hi:[0,0,1]
	v_pk_fma_f32 v[90:91], v[90:91], v[218:219], v[240:241] neg_lo:[0,0,1] neg_hi:[0,0,1]
	ds_read_b128 v[216:219], v74 offset:31488
	v_pk_fma_f32 v[64:65], v[234:235], v[92:93], v[64:65]
	v_pk_mul_f32 v[66:67], v[232:233], v[88:89]
	v_pk_fma_f32 v[66:67], v[234:235], v[90:91], v[66:67]
	ds_read_b128 v[232:235], v74 offset:32512
	v_add_f32_e32 v146, v64, v65
	v_add_f32_e32 v167, v66, v67
	s_waitcnt lgkmcnt(6)
	v_pk_mul_f32 v[60:61], v[94:95], v[126:127]
	v_pk_mul_f32 v[62:63], v[88:89], v[126:127]
	v_pk_fma_f32 v[60:61], v[92:93], v[128:129], v[60:61]
	v_pk_fma_f32 v[62:63], v[90:91], v[128:129], v[62:63]
	v_add_f32_e32 v60, v60, v61
	v_add_f32_e32 v62, v62, v63
	v_pk_mul_f32 v[94:95], v[94:95], v[122:123]
	v_pk_mul_f32 v[92:93], v[92:93], v[124:125]
	v_add_f32_dpp v60, v60, v60 quad_perm:[1,0,3,2] row_mask:0xf bank_mask:0xf bound_ctrl:1
	v_add_f32_dpp v62, v62, v62 quad_perm:[1,0,3,2] row_mask:0xf bank_mask:0xf bound_ctrl:1
	v_pk_fma_f32 v[94:95], v[142:143], v[134:135], v[94:95] op_sel_hi:[0,1,1]
	v_add_f32_dpp v60, v60, v60 quad_perm:[2,3,0,1] row_mask:0xf bank_mask:0xf bound_ctrl:1
	v_add_f32_dpp v62, v62, v62 quad_perm:[2,3,0,1] row_mask:0xf bank_mask:0xf bound_ctrl:1
	v_pk_fma_f32 v[92:93], v[142:143], v[136:137], v[92:93] op_sel_hi:[0,1,1]
	v_add_f32_dpp v60, v60, v60 row_half_mirror row_mask:0xf bank_mask:0xf bound_ctrl:1
	v_add_f32_dpp v62, v62, v62 row_half_mirror row_mask:0xf bank_mask:0xf bound_ctrl:1
	ds_read_b128 v[126:129], v74 offset:33280
	v_add_f32_dpp v60, v60, v60 row_mirror row_mask:0xf bank_mask:0xf bound_ctrl:1
	v_add_f32_dpp v62, v62, v62 row_mirror row_mask:0xf bank_mask:0xf bound_ctrl:1
	ds_read_b128 v[134:137], v74 offset:33792
	ds_read_b32 v142, v75 offset:34304
	v_pk_fma_f32 v[94:95], v[130:131], v[60:61], v[94:95] op_sel_hi:[1,0,1] neg_lo:[1,0,0] neg_hi:[1,0,0]
	v_pk_fma_f32 v[92:93], v[132:133], v[60:61], v[92:93] op_sel_hi:[1,0,1] neg_lo:[1,0,0] neg_hi:[1,0,0]
	v_pk_mul_f32 v[238:239], v[130:131], v[62:63] op_sel_hi:[1,0]
	v_pk_mul_f32 v[240:241], v[132:133], v[62:63] op_sel_hi:[1,0]
	ds_read_b128 v[130:133], v74 offset:33536
	v_pk_mul_f32 v[64:65], v[138:139], v[94:95]
	v_pk_fma_f32 v[88:89], v[88:89], v[122:123], v[238:239] neg_lo:[0,0,1] neg_hi:[0,0,1]
	v_pk_fma_f32 v[90:91], v[90:91], v[124:125], v[240:241] neg_lo:[0,0,1] neg_hi:[0,0,1]
	ds_read_b128 v[122:125], v74 offset:33024
	v_pk_fma_f32 v[64:65], v[140:141], v[92:93], v[64:65]
	v_pk_mul_f32 v[66:67], v[138:139], v[88:89]
	v_pk_fma_f32 v[66:67], v[140:141], v[90:91], v[66:67]
	ds_read_b128 v[138:141], v74 offset:34048
	v_add_f32_e32 v147, v64, v65
	v_add_f32_e32 v168, v66, v67
	s_waitcnt lgkmcnt(6)
	v_pk_mul_f32 v[60:61], v[94:95], v[220:221]
	v_pk_mul_f32 v[62:63], v[88:89], v[220:221]
	v_pk_fma_f32 v[60:61], v[92:93], v[222:223], v[60:61]
	v_pk_fma_f32 v[62:63], v[90:91], v[222:223], v[62:63]
	v_add_f32_e32 v60, v60, v61
	v_add_f32_e32 v62, v62, v63
	v_pk_mul_f32 v[94:95], v[94:95], v[216:217]
	v_pk_mul_f32 v[92:93], v[92:93], v[218:219]
	v_add_f32_dpp v60, v60, v60 quad_perm:[1,0,3,2] row_mask:0xf bank_mask:0xf bound_ctrl:1
	v_add_f32_dpp v62, v62, v62 quad_perm:[1,0,3,2] row_mask:0xf bank_mask:0xf bound_ctrl:1
	v_pk_fma_f32 v[94:95], v[236:237], v[228:229], v[94:95] op_sel_hi:[0,1,1]
	v_add_f32_dpp v60, v60, v60 quad_perm:[2,3,0,1] row_mask:0xf bank_mask:0xf bound_ctrl:1
	v_add_f32_dpp v62, v62, v62 quad_perm:[2,3,0,1] row_mask:0xf bank_mask:0xf bound_ctrl:1
	v_pk_fma_f32 v[92:93], v[236:237], v[230:231], v[92:93] op_sel_hi:[0,1,1]
	v_add_f32_dpp v60, v60, v60 row_half_mirror row_mask:0xf bank_mask:0xf bound_ctrl:1
	v_add_f32_dpp v62, v62, v62 row_half_mirror row_mask:0xf bank_mask:0xf bound_ctrl:1
	ds_read_b128 v[220:223], v74 offset:34816
	v_add_f32_dpp v60, v60, v60 row_mirror row_mask:0xf bank_mask:0xf bound_ctrl:1
	v_add_f32_dpp v62, v62, v62 row_mirror row_mask:0xf bank_mask:0xf bound_ctrl:1
	ds_read_b128 v[228:231], v74 offset:35328
	ds_read_b32 v236, v75 offset:35840
	v_pk_fma_f32 v[94:95], v[224:225], v[60:61], v[94:95] op_sel_hi:[1,0,1] neg_lo:[1,0,0] neg_hi:[1,0,0]
	v_pk_fma_f32 v[92:93], v[226:227], v[60:61], v[92:93] op_sel_hi:[1,0,1] neg_lo:[1,0,0] neg_hi:[1,0,0]
	v_pk_mul_f32 v[238:239], v[224:225], v[62:63] op_sel_hi:[1,0]
	v_pk_mul_f32 v[240:241], v[226:227], v[62:63] op_sel_hi:[1,0]
	ds_read_b128 v[224:227], v74 offset:35072
	v_pk_mul_f32 v[64:65], v[232:233], v[94:95]
	v_pk_fma_f32 v[88:89], v[88:89], v[216:217], v[238:239] neg_lo:[0,0,1] neg_hi:[0,0,1]
	v_pk_fma_f32 v[90:91], v[90:91], v[218:219], v[240:241] neg_lo:[0,0,1] neg_hi:[0,0,1]
	ds_read_b128 v[216:219], v74 offset:34560
	v_pk_fma_f32 v[64:65], v[234:235], v[92:93], v[64:65]
	v_pk_mul_f32 v[66:67], v[232:233], v[88:89]
	v_pk_fma_f32 v[66:67], v[234:235], v[90:91], v[66:67]
	ds_read_b128 v[232:235], v74 offset:35584
	v_add_f32_e32 v148, v64, v65
	v_add_f32_e32 v169, v66, v67
	s_waitcnt lgkmcnt(6)
; template <bool DUAL>
; __device__ __forceinline__ void rwkv_tile(const Params& p, int l, int tile, unsigned char* smem) {
;     ...
; #pragma unroll 2
;       for (int i = 0; i < 32; ++i) {
;         const int inx = (i + 1) & 31;
;         const float4 nw4 = *(const float4*)(rp + inx * 384), nkk4 = *(const float4*)(rp + inx * 384 + 64), nkb4 = *(const float4*)(rp + inx * 384 + 128);
;         const float4 nkd4 = *(const float4*)(rp + inx * 384 + 192), nr4 = *(const float4*)(rp + inx * 384 + 256);
;         const float nv = vp[inx * 384];
;         v2f t = sA * (v2f){kk4.x, kk4.y};
;         t = sB * (v2f){kk4.z, kk4.w} + t;
;         float sa = t.x + t.y, ia = 0.f;
;         if (DUAL) {
;           v2f ti = iA * (v2f){kk4.x, kk4.y};
;           ti = iB * (v2f){kk4.z, kk4.w} + ti;
;           ia = ti.x + ti.y;
;           sa += dppf<0xB1>(sa); ia += dppf<0xB1>(ia);
;           sa += dppf<0x4E>(sa); ia += dppf<0x4E>(ia);
;           sa += dppf<0x141>(sa); ia += dppf<0x141>(ia);
;           sa += dppf<0x140>(sa); ia += dppf<0x140>(ia);
;         } else {
;           sa = sum16(sa);
;         }
;         v2f cA = sA * (v2f){w4.x, w4.y} + (v2f){kd4.x, kd4.y} * v;
;         v2f cB = sB * (v2f){w4.z, w4.w} + (v2f){kd4.z, kd4.w} * v;
;         sA = cA - (v2f){kb4.x, kb4.y} * sa;
;         sB = cB - (v2f){kb4.z, kb4.w} * sa;
;         v2f u = sA * (v2f){r4.x, r4.y};
;         u = sB * (v2f){r4.z, r4.w} + u;
;         float y = u.x + u.y, g = 0.f;
;         if (DUAL) {
;           iA = iA * (v2f){w4.x, w4.y} - (v2f){kb4.x, kb4.y} * ia;
;           iB = iB * (v2f){w4.z, w4.w} - (v2f){kb4.z, kb4.w} * ia;
;           v2f ui = iA * (v2f){r4.x, r4.y};
;           ui = iB * (v2f){r4.z, r4.w} + ui;
;           g = ui.x + ui.y;
;           y += dppf<0xB1>(y); g += dppf<0xB1>(g);
;           y += dppf<0x4E>(y); g += dppf<0x4E>(g);
;           y += dppf<0x141>(y); g += dppf<0x141>(g);
;           y += dppf<0x140>(y); g += dppf<0x140>(g);
;           if (fr == (i & 15)) gkeep = g;
;         } else {
;           y = sum16(y);
;         }
;         if (fr == (i & 15)) ykeep = y;
	v_pk_mul_f32 v[60:61], v[94:95], v[126:127]
	v_pk_mul_f32 v[62:63], v[88:89], v[126:127]
	v_pk_fma_f32 v[60:61], v[92:93], v[128:129], v[60:61]
	v_pk_fma_f32 v[62:63], v[90:91], v[128:129], v[62:63]
	v_add_f32_e32 v60, v60, v61
	v_add_f32_e32 v62, v62, v63
	v_pk_mul_f32 v[94:95], v[94:95], v[122:123]
	v_pk_mul_f32 v[92:93], v[92:93], v[124:125]
	v_add_f32_dpp v60, v60, v60 quad_perm:[1,0,3,2] row_mask:0xf bank_mask:0xf bound_ctrl:1
	v_add_f32_dpp v62, v62, v62 quad_perm:[1,0,3,2] row_mask:0xf bank_mask:0xf bound_ctrl:1
	v_pk_fma_f32 v[94:95], v[142:143], v[134:135], v[94:95] op_sel_hi:[0,1,1]
	v_add_f32_dpp v60, v60, v60 quad_perm:[2,3,0,1] row_mask:0xf bank_mask:0xf bound_ctrl:1
	v_add_f32_dpp v62, v62, v62 quad_perm:[2,3,0,1] row_mask:0xf bank_mask:0xf bound_ctrl:1
	v_pk_fma_f32 v[92:93], v[142:143], v[136:137], v[92:93] op_sel_hi:[0,1,1]
	v_add_f32_dpp v60, v60, v60 row_half_mirror row_mask:0xf bank_mask:0xf bound_ctrl:1
	v_add_f32_dpp v62, v62, v62 row_half_mirror row_mask:0xf bank_mask:0xf bound_ctrl:1
	ds_read_b128 v[126:129], v74 offset:36352
	v_add_f32_dpp v60, v60, v60 row_mirror row_mask:0xf bank_mask:0xf bound_ctrl:1
	v_add_f32_dpp v62, v62, v62 row_mirror row_mask:0xf bank_mask:0xf bound_ctrl:1
	ds_read_b128 v[134:137], v74 offset:36864
	ds_read_b32 v142, v75 offset:37376
	v_pk_fma_f32 v[94:95], v[130:131], v[60:61], v[94:95] op_sel_hi:[1,0,1] neg_lo:[1,0,0] neg_hi:[1,0,0]
	v_pk_fma_f32 v[92:93], v[132:133], v[60:61], v[92:93] op_sel_hi:[1,0,1] neg_lo:[1,0,0] neg_hi:[1,0,0]
	v_pk_mul_f32 v[238:239], v[130:131], v[62:63] op_sel_hi:[1,0]
	v_pk_mul_f32 v[240:241], v[132:133], v[62:63] op_sel_hi:[1,0]
	ds_read_b128 v[130:133], v74 offset:36608
	v_pk_mul_f32 v[64:65], v[138:139], v[94:95]
	v_pk_fma_f32 v[88:89], v[88:89], v[122:123], v[238:239] neg_lo:[0,0,1] neg_hi:[0,0,1]
	v_pk_fma_f32 v[90:91], v[90:91], v[124:125], v[240:241] neg_lo:[0,0,1] neg_hi:[0,0,1]
	ds_read_b128 v[122:125], v74 offset:36096
	v_pk_fma_f32 v[64:65], v[140:141], v[92:93], v[64:65]
	v_pk_mul_f32 v[66:67], v[138:139], v[88:89]
	v_pk_fma_f32 v[66:67], v[140:141], v[90:91], v[66:67]
	ds_read_b128 v[138:141], v74 offset:37120
	v_add_f32_e32 v149, v64, v65
	v_add_f32_e32 v170, v66, v67
	s_waitcnt lgkmcnt(6)
	v_pk_mul_f32 v[60:61], v[94:95], v[220:221]
	v_pk_mul_f32 v[62:63], v[88:89], v[220:221]
	v_pk_fma_f32 v[60:61], v[92:93], v[222:223], v[60:61]
	v_pk_fma_f32 v[62:63], v[90:91], v[222:223], v[62:63]
	v_add_f32_e32 v60, v60, v61
	v_add_f32_e32 v62, v62, v63
	v_pk_mul_f32 v[94:95], v[94:95], v[216:217]
	v_pk_mul_f32 v[92:93], v[92:93], v[218:219]
	v_add_f32_dpp v60, v60, v60 quad_perm:[1,0,3,2] row_mask:0xf bank_mask:0xf bound_ctrl:1
	v_add_f32_dpp v62, v62, v62 quad_perm:[1,0,3,2] row_mask:0xf bank_mask:0xf bound_ctrl:1
	v_pk_fma_f32 v[94:95], v[236:237], v[228:229], v[94:95] op_sel_hi:[0,1,1]
	v_add_f32_dpp v60, v60, v60 quad_perm:[2,3,0,1] row_mask:0xf bank_mask:0xf bound_ctrl:1
	v_add_f32_dpp v62, v62, v62 quad_perm:[2,3,0,1] row_mask:0xf bank_mask:0xf bound_ctrl:1
	v_pk_fma_f32 v[92:93], v[236:237], v[230:231], v[92:93] op_sel_hi:[0,1,1]
	v_add_f32_dpp v60, v60, v60 row_half_mirror row_mask:0xf bank_mask:0xf bound_ctrl:1
	v_add_f32_dpp v62, v62, v62 row_half_mirror row_mask:0xf bank_mask:0xf bound_ctrl:1
	ds_read_b128 v[220:223], v74 offset:37888
	v_add_f32_dpp v60, v60, v60 row_mirror row_mask:0xf bank_mask:0xf bound_ctrl:1
	v_add_f32_dpp v62, v62, v62 row_mirror row_mask:0xf bank_mask:0xf bound_ctrl:1
	ds_read_b128 v[228:231], v74 offset:38400
	ds_read_b32 v236, v75 offset:38912
	v_pk_fma_f32 v[94:95], v[224:225], v[60:61], v[94:95] op_sel_hi:[1,0,1] neg_lo:[1,0,0] neg_hi:[1,0,0]
	v_pk_fma_f32 v[92:93], v[226:227], v[60:61], v[92:93] op_sel_hi:[1,0,1] neg_lo:[1,0,0] neg_hi:[1,0,0]
	v_pk_mul_f32 v[238:239], v[224:225], v[62:63] op_sel_hi:[1,0]
	v_pk_mul_f32 v[240:241], v[226:227], v[62:63] op_sel_hi:[1,0]
	ds_read_b128 v[224:227], v74 offset:38144
	v_pk_mul_f32 v[64:65], v[232:233], v[94:95]
	v_pk_fma_f32 v[88:89], v[88:89], v[216:217], v[238:239] neg_lo:[0,0,1] neg_hi:[0,0,1]
	v_pk_fma_f32 v[90:91], v[90:91], v[218:219], v[240:241] neg_lo:[0,0,1] neg_hi:[0,0,1]
	ds_read_b128 v[216:219], v74 offset:37632
	v_pk_fma_f32 v[64:65], v[234:235], v[92:93], v[64:65]
	v_pk_mul_f32 v[66:67], v[232:233], v[88:89]
	v_pk_fma_f32 v[66:67], v[234:235], v[90:91], v[66:67]
	ds_read_b128 v[232:235], v74 offset:38656
	v_add_f32_e32 v150, v64, v65
	v_add_f32_e32 v171, v66, v67
	s_waitcnt lgkmcnt(6)
	v_pk_mul_f32 v[60:61], v[94:95], v[126:127]
	v_pk_mul_f32 v[62:63], v[88:89], v[126:127]
	v_pk_fma_f32 v[60:61], v[92:93], v[128:129], v[60:61]
	v_pk_fma_f32 v[62:63], v[90:91], v[128:129], v[62:63]
	v_add_f32_e32 v60, v60, v61
	v_add_f32_e32 v62, v62, v63
	v_pk_mul_f32 v[94:95], v[94:95], v[122:123]
	v_pk_mul_f32 v[92:93], v[92:93], v[124:125]
	v_add_f32_dpp v60, v60, v60 quad_perm:[1,0,3,2] row_mask:0xf bank_mask:0xf bound_ctrl:1
	v_add_f32_dpp v62, v62, v62 quad_perm:[1,0,3,2] row_mask:0xf bank_mask:0xf bound_ctrl:1
	v_pk_fma_f32 v[94:95], v[142:143], v[134:135], v[94:95] op_sel_hi:[0,1,1]
	v_add_f32_dpp v60, v60, v60 quad_perm:[2,3,0,1] row_mask:0xf bank_mask:0xf bound_ctrl:1
	v_add_f32_dpp v62, v62, v62 quad_perm:[2,3,0,1] row_mask:0xf bank_mask:0xf bound_ctrl:1
	v_pk_fma_f32 v[92:93], v[142:143], v[136:137], v[92:93] op_sel_hi:[0,1,1]
	v_add_f32_dpp v60, v60, v60 row_half_mirror row_mask:0xf bank_mask:0xf bound_ctrl:1
	v_add_f32_dpp v62, v62, v62 row_half_mirror row_mask:0xf bank_mask:0xf bound_ctrl:1
	ds_read_b128 v[126:129], v74 offset:39424
	v_add_f32_dpp v60, v60, v60 row_mirror row_mask:0xf bank_mask:0xf bound_ctrl:1
	v_add_f32_dpp v62, v62, v62 row_mirror row_mask:0xf bank_mask:0xf bound_ctrl:1
	ds_read_b128 v[134:137], v74 offset:39936
	ds_read_b32 v142, v75 offset:40448
	v_pk_fma_f32 v[94:95], v[130:131], v[60:61], v[94:95] op_sel_hi:[1,0,1] neg_lo:[1,0,0] neg_hi:[1,0,0]
	v_pk_fma_f32 v[92:93], v[132:133], v[60:61], v[92:93] op_sel_hi:[1,0,1] neg_lo:[1,0,0] neg_hi:[1,0,0]
	v_pk_mul_f32 v[238:239], v[130:131], v[62:63] op_sel_hi:[1,0]
	v_pk_mul_f32 v[240:241], v[132:133], v[62:63] op_sel_hi:[1,0]
	ds_read_b128 v[130:133], v74 offset:39680
	v_pk_mul_f32 v[64:65], v[138:139], v[94:95]
	v_pk_fma_f32 v[88:89], v[88:89], v[122:123], v[238:239] neg_lo:[0,0,1] neg_hi:[0,0,1]
	v_pk_fma_f32 v[90:91], v[90:91], v[124:125], v[240:241] neg_lo:[0,0,1] neg_hi:[0,0,1]
	ds_read_b128 v[122:125], v74 offset:39168
	v_pk_fma_f32 v[64:65], v[140:141], v[92:93], v[64:65]
	v_pk_mul_f32 v[66:67], v[138:139], v[88:89]
	v_pk_fma_f32 v[66:67], v[140:141], v[90:91], v[66:67]
	ds_read_b128 v[138:141], v74 offset:40192
	v_add_f32_e32 v151, v64, v65
	v_add_f32_e32 v172, v66, v67
	s_waitcnt lgkmcnt(6)
; template <bool DUAL>
; __device__ __forceinline__ void rwkv_tile(const Params& p, int l, int tile, unsigned char* smem) {
;     ...
; #pragma unroll 2
;       for (int i = 0; i < 32; ++i) {
;         const int inx = (i + 1) & 31;
;         const float4 nw4 = *(const float4*)(rp + inx * 384), nkk4 = *(const float4*)(rp + inx * 384 + 64), nkb4 = *(const float4*)(rp + inx * 384 + 128);
;         const float4 nkd4 = *(const float4*)(rp + inx * 384 + 192), nr4 = *(const float4*)(rp + inx * 384 + 256);
;         const float nv = vp[inx * 384];
;         v2f t = sA * (v2f){kk4.x, kk4.y};
;         t = sB * (v2f){kk4.z, kk4.w} + t;
;         float sa = t.x + t.y, ia = 0.f;
;         if (DUAL) {
;           v2f ti = iA * (v2f){kk4.x, kk4.y};
;           ti = iB * (v2f){kk4.z, kk4.w} + ti;
;           ia = ti.x + ti.y;
;           sa += dppf<0xB1>(sa); ia += dppf<0xB1>(ia);
;           sa += dppf<0x4E>(sa); ia += dppf<0x4E>(ia);
;           sa += dppf<0x141>(sa); ia += dppf<0x141>(ia);
;           sa += dppf<0x140>(sa); ia += dppf<0x140>(ia);
;         } else {
;           sa = sum16(sa);
;         }
;         v2f cA = sA * (v2f){w4.x, w4.y} + (v2f){kd4.x, kd4.y} * v;
;         v2f cB = sB * (v2f){w4.z, w4.w} + (v2f){kd4.z, kd4.w} * v;
;         sA = cA - (v2f){kb4.x, kb4.y} * sa;
;         sB = cB - (v2f){kb4.z, kb4.w} * sa;
;         v2f u = sA * (v2f){r4.x, r4.y};
;         u = sB * (v2f){r4.z, r4.w} + u;
;         float y = u.x + u.y, g = 0.f;
;         if (DUAL) {
;           iA = iA * (v2f){w4.x, w4.y} - (v2f){kb4.x, kb4.y} * ia;
;           iB = iB * (v2f){w4.z, w4.w} - (v2f){kb4.z, kb4.w} * ia;
;           v2f ui = iA * (v2f){r4.x, r4.y};
;           ui = iB * (v2f){r4.z, r4.w} + ui;
;           g = ui.x + ui.y;
;           y += dppf<0xB1>(y); g += dppf<0xB1>(g);
;           y += dppf<0x4E>(y); g += dppf<0x4E>(g);
;           y += dppf<0x141>(y); g += dppf<0x141>(g);
;           y += dppf<0x140>(y); g += dppf<0x140>(g);
;           if (fr == (i & 15)) gkeep = g;
;         } else {
;           y = sum16(y);
;         }
;         if (fr == (i & 15)) ykeep = y;
	v_pk_mul_f32 v[60:61], v[94:95], v[220:221]
	v_pk_mul_f32 v[62:63], v[88:89], v[220:221]
	v_pk_fma_f32 v[60:61], v[92:93], v[222:223], v[60:61]
	v_pk_fma_f32 v[62:63], v[90:91], v[222:223], v[62:63]
	v_add_f32_e32 v60, v60, v61
	v_add_f32_e32 v62, v62, v63
	v_pk_mul_f32 v[94:95], v[94:95], v[216:217]
	v_pk_mul_f32 v[92:93], v[92:93], v[218:219]
	v_add_f32_dpp v60, v60, v60 quad_perm:[1,0,3,2] row_mask:0xf bank_mask:0xf bound_ctrl:1
	v_add_f32_dpp v62, v62, v62 quad_perm:[1,0,3,2] row_mask:0xf bank_mask:0xf bound_ctrl:1
	v_pk_fma_f32 v[94:95], v[236:237], v[228:229], v[94:95] op_sel_hi:[0,1,1]
	v_add_f32_dpp v60, v60, v60 quad_perm:[2,3,0,1] row_mask:0xf bank_mask:0xf bound_ctrl:1
	v_add_f32_dpp v62, v62, v62 quad_perm:[2,3,0,1] row_mask:0xf bank_mask:0xf bound_ctrl:1
	v_pk_fma_f32 v[92:93], v[236:237], v[230:231], v[92:93] op_sel_hi:[0,1,1]
	v_add_f32_dpp v60, v60, v60 row_half_mirror row_mask:0xf bank_mask:0xf bound_ctrl:1
	v_add_f32_dpp v62, v62, v62 row_half_mirror row_mask:0xf bank_mask:0xf bound_ctrl:1
	ds_read_b128 v[220:223], v74 offset:40960
	v_add_f32_dpp v60, v60, v60 row_mirror row_mask:0xf bank_mask:0xf bound_ctrl:1
	v_add_f32_dpp v62, v62, v62 row_mirror row_mask:0xf bank_mask:0xf bound_ctrl:1
	ds_read_b128 v[228:231], v74 offset:41472
	ds_read_b32 v236, v75 offset:41984
	v_pk_fma_f32 v[94:95], v[224:225], v[60:61], v[94:95] op_sel_hi:[1,0,1] neg_lo:[1,0,0] neg_hi:[1,0,0]
	v_pk_fma_f32 v[92:93], v[226:227], v[60:61], v[92:93] op_sel_hi:[1,0,1] neg_lo:[1,0,0] neg_hi:[1,0,0]
	v_pk_mul_f32 v[238:239], v[224:225], v[62:63] op_sel_hi:[1,0]
	v_pk_mul_f32 v[240:241], v[226:227], v[62:63] op_sel_hi:[1,0]
	ds_read_b128 v[224:227], v74 offset:41216
	v_pk_mul_f32 v[64:65], v[232:233], v[94:95]
	v_pk_fma_f32 v[88:89], v[88:89], v[216:217], v[238:239] neg_lo:[0,0,1] neg_hi:[0,0,1]
	v_pk_fma_f32 v[90:91], v[90:91], v[218:219], v[240:241] neg_lo:[0,0,1] neg_hi:[0,0,1]
	ds_read_b128 v[216:219], v74 offset:40704
	v_pk_fma_f32 v[64:65], v[234:235], v[92:93], v[64:65]
	v_pk_mul_f32 v[66:67], v[232:233], v[88:89]
	v_pk_fma_f32 v[66:67], v[234:235], v[90:91], v[66:67]
	ds_read_b128 v[232:235], v74 offset:41728
	v_add_f32_e32 v152, v64, v65
	v_add_f32_e32 v173, v66, v67
	s_waitcnt lgkmcnt(6)
	v_pk_mul_f32 v[60:61], v[94:95], v[126:127]
	v_pk_mul_f32 v[62:63], v[88:89], v[126:127]
	v_pk_fma_f32 v[60:61], v[92:93], v[128:129], v[60:61]
	v_pk_fma_f32 v[62:63], v[90:91], v[128:129], v[62:63]
	v_add_f32_e32 v60, v60, v61
	v_add_f32_e32 v62, v62, v63
	v_pk_mul_f32 v[94:95], v[94:95], v[122:123]
	v_pk_mul_f32 v[92:93], v[92:93], v[124:125]
	v_add_f32_dpp v60, v60, v60 quad_perm:[1,0,3,2] row_mask:0xf bank_mask:0xf bound_ctrl:1
	v_add_f32_dpp v62, v62, v62 quad_perm:[1,0,3,2] row_mask:0xf bank_mask:0xf bound_ctrl:1
	v_pk_fma_f32 v[94:95], v[142:143], v[134:135], v[94:95] op_sel_hi:[0,1,1]
	v_add_f32_dpp v60, v60, v60 quad_perm:[2,3,0,1] row_mask:0xf bank_mask:0xf bound_ctrl:1
	v_add_f32_dpp v62, v62, v62 quad_perm:[2,3,0,1] row_mask:0xf bank_mask:0xf bound_ctrl:1
	v_pk_fma_f32 v[92:93], v[142:143], v[136:137], v[92:93] op_sel_hi:[0,1,1]
	v_add_f32_dpp v60, v60, v60 row_half_mirror row_mask:0xf bank_mask:0xf bound_ctrl:1
	v_add_f32_dpp v62, v62, v62 row_half_mirror row_mask:0xf bank_mask:0xf bound_ctrl:1
	ds_read_b128 v[126:129], v74 offset:42496
	v_add_f32_dpp v60, v60, v60 row_mirror row_mask:0xf bank_mask:0xf bound_ctrl:1
	v_add_f32_dpp v62, v62, v62 row_mirror row_mask:0xf bank_mask:0xf bound_ctrl:1
	ds_read_b128 v[134:137], v74 offset:43008
	ds_read_b32 v142, v75 offset:43520
	v_pk_fma_f32 v[94:95], v[130:131], v[60:61], v[94:95] op_sel_hi:[1,0,1] neg_lo:[1,0,0] neg_hi:[1,0,0]
	v_pk_fma_f32 v[92:93], v[132:133], v[60:61], v[92:93] op_sel_hi:[1,0,1] neg_lo:[1,0,0] neg_hi:[1,0,0]
	v_pk_mul_f32 v[238:239], v[130:131], v[62:63] op_sel_hi:[1,0]
	v_pk_mul_f32 v[240:241], v[132:133], v[62:63] op_sel_hi:[1,0]
	ds_read_b128 v[130:133], v74 offset:42752
	v_pk_mul_f32 v[64:65], v[138:139], v[94:95]
	v_pk_fma_f32 v[88:89], v[88:89], v[122:123], v[238:239] neg_lo:[0,0,1] neg_hi:[0,0,1]
	v_pk_fma_f32 v[90:91], v[90:91], v[124:125], v[240:241] neg_lo:[0,0,1] neg_hi:[0,0,1]
	ds_read_b128 v[122:125], v74 offset:42240
	v_pk_fma_f32 v[64:65], v[140:141], v[92:93], v[64:65]
	v_pk_mul_f32 v[66:67], v[138:139], v[88:89]
	v_pk_fma_f32 v[66:67], v[140:141], v[90:91], v[66:67]
	ds_read_b128 v[138:141], v74 offset:43264
	v_add_f32_e32 v153, v64, v65
	v_add_f32_e32 v174, v66, v67
	s_waitcnt lgkmcnt(6)
	v_pk_mul_f32 v[60:61], v[94:95], v[220:221]
	v_pk_mul_f32 v[62:63], v[88:89], v[220:221]
	v_pk_fma_f32 v[60:61], v[92:93], v[222:223], v[60:61]
	v_pk_fma_f32 v[62:63], v[90:91], v[222:223], v[62:63]
	v_add_f32_e32 v60, v60, v61
	v_add_f32_e32 v62, v62, v63
	v_pk_mul_f32 v[94:95], v[94:95], v[216:217]
	v_pk_mul_f32 v[92:93], v[92:93], v[218:219]
	v_add_f32_dpp v60, v60, v60 quad_perm:[1,0,3,2] row_mask:0xf bank_mask:0xf bound_ctrl:1
	v_add_f32_dpp v62, v62, v62 quad_perm:[1,0,3,2] row_mask:0xf bank_mask:0xf bound_ctrl:1
	v_pk_fma_f32 v[94:95], v[236:237], v[228:229], v[94:95] op_sel_hi:[0,1,1]
	v_add_f32_dpp v60, v60, v60 quad_perm:[2,3,0,1] row_mask:0xf bank_mask:0xf bound_ctrl:1
	v_add_f32_dpp v62, v62, v62 quad_perm:[2,3,0,1] row_mask:0xf bank_mask:0xf bound_ctrl:1
	v_pk_fma_f32 v[92:93], v[236:237], v[230:231], v[92:93] op_sel_hi:[0,1,1]
	v_add_f32_dpp v60, v60, v60 row_half_mirror row_mask:0xf bank_mask:0xf bound_ctrl:1
	v_add_f32_dpp v62, v62, v62 row_half_mirror row_mask:0xf bank_mask:0xf bound_ctrl:1
	ds_read_b128 v[220:223], v74 offset:44032
	v_add_f32_dpp v60, v60, v60 row_mirror row_mask:0xf bank_mask:0xf bound_ctrl:1
	v_add_f32_dpp v62, v62, v62 row_mirror row_mask:0xf bank_mask:0xf bound_ctrl:1
	ds_read_b128 v[228:231], v74 offset:44544
	ds_read_b32 v236, v75 offset:45056
	v_pk_fma_f32 v[94:95], v[224:225], v[60:61], v[94:95] op_sel_hi:[1,0,1] neg_lo:[1,0,0] neg_hi:[1,0,0]
	v_pk_fma_f32 v[92:93], v[226:227], v[60:61], v[92:93] op_sel_hi:[1,0,1] neg_lo:[1,0,0] neg_hi:[1,0,0]
	v_pk_mul_f32 v[238:239], v[224:225], v[62:63] op_sel_hi:[1,0]
	v_pk_mul_f32 v[240:241], v[226:227], v[62:63] op_sel_hi:[1,0]
	ds_read_b128 v[224:227], v74 offset:44288
	v_pk_mul_f32 v[64:65], v[232:233], v[94:95]
	v_pk_fma_f32 v[88:89], v[88:89], v[216:217], v[238:239] neg_lo:[0,0,1] neg_hi:[0,0,1]
	v_pk_fma_f32 v[90:91], v[90:91], v[218:219], v[240:241] neg_lo:[0,0,1] neg_hi:[0,0,1]
	ds_read_b128 v[216:219], v74 offset:43776
	v_pk_fma_f32 v[64:65], v[234:235], v[92:93], v[64:65]
	v_pk_mul_f32 v[66:67], v[232:233], v[88:89]
	v_pk_fma_f32 v[66:67], v[234:235], v[90:91], v[66:67]
	ds_read_b128 v[232:235], v74 offset:44800
	v_add_f32_e32 v154, v64, v65
	v_add_f32_e32 v175, v66, v67
	s_waitcnt lgkmcnt(6)
; template <bool DUAL>
; __device__ __forceinline__ void rwkv_tile(const Params& p, int l, int tile, unsigned char* smem) {
;     ...
; #pragma unroll 2
;       for (int i = 0; i < 32; ++i) {
;         const int inx = (i + 1) & 31;
;         const float4 nw4 = *(const float4*)(rp + inx * 384), nkk4 = *(const float4*)(rp + inx * 384 + 64), nkb4 = *(const float4*)(rp + inx * 384 + 128);
;         const float4 nkd4 = *(const float4*)(rp + inx * 384 + 192), nr4 = *(const float4*)(rp + inx * 384 + 256);
;         const float nv = vp[inx * 384];
;         v2f t = sA * (v2f){kk4.x, kk4.y};
;         t = sB * (v2f){kk4.z, kk4.w} + t;
;         float sa = t.x + t.y, ia = 0.f;
;         if (DUAL) {
;           v2f ti = iA * (v2f){kk4.x, kk4.y};
;           ti = iB * (v2f){kk4.z, kk4.w} + ti;
;           ia = ti.x + ti.y;
;           sa += dppf<0xB1>(sa); ia += dppf<0xB1>(ia);
;           sa += dppf<0x4E>(sa); ia += dppf<0x4E>(ia);
;           sa += dppf<0x141>(sa); ia += dppf<0x141>(ia);
;           sa += dppf<0x140>(sa); ia += dppf<0x140>(ia);
;         } else {
;           sa = sum16(sa);
;         }
;         v2f cA = sA * (v2f){w4.x, w4.y} + (v2f){kd4.x, kd4.y} * v;
;         v2f cB = sB * (v2f){w4.z, w4.w} + (v2f){kd4.z, kd4.w} * v;
;         sA = cA - (v2f){kb4.x, kb4.y} * sa;
;         sB = cB - (v2f){kb4.z, kb4.w} * sa;
;         v2f u = sA * (v2f){r4.x, r4.y};
;         u = sB * (v2f){r4.z, r4.w} + u;
;         float y = u.x + u.y, g = 0.f;
;         if (DUAL) {
;           iA = iA * (v2f){w4.x, w4.y} - (v2f){kb4.x, kb4.y} * ia;
;           iB = iB * (v2f){w4.z, w4.w} - (v2f){kb4.z, kb4.w} * ia;
;           v2f ui = iA * (v2f){r4.x, r4.y};
;           ui = iB * (v2f){r4.z, r4.w} + ui;
;           g = ui.x + ui.y;
;           y += dppf<0xB1>(y); g += dppf<0xB1>(g);
;           y += dppf<0x4E>(y); g += dppf<0x4E>(g);
;           y += dppf<0x141>(y); g += dppf<0x141>(g);
;           y += dppf<0x140>(y); g += dppf<0x140>(g);
;           if (fr == (i & 15)) gkeep = g;
;         } else {
;           y = sum16(y);
;         }
;         if (fr == (i & 15)) ykeep = y;
	v_pk_mul_f32 v[60:61], v[94:95], v[126:127]
	v_pk_mul_f32 v[62:63], v[88:89], v[126:127]
	v_pk_fma_f32 v[60:61], v[92:93], v[128:129], v[60:61]
	v_pk_fma_f32 v[62:63], v[90:91], v[128:129], v[62:63]
	v_add_f32_e32 v60, v60, v61
	v_add_f32_e32 v62, v62, v63
	v_pk_mul_f32 v[94:95], v[94:95], v[122:123]
	v_pk_mul_f32 v[92:93], v[92:93], v[124:125]
	v_add_f32_dpp v60, v60, v60 quad_perm:[1,0,3,2] row_mask:0xf bank_mask:0xf bound_ctrl:1
	v_add_f32_dpp v62, v62, v62 quad_perm:[1,0,3,2] row_mask:0xf bank_mask:0xf bound_ctrl:1
	v_pk_fma_f32 v[94:95], v[142:143], v[134:135], v[94:95] op_sel_hi:[0,1,1]
	v_add_f32_dpp v60, v60, v60 quad_perm:[2,3,0,1] row_mask:0xf bank_mask:0xf bound_ctrl:1
	v_add_f32_dpp v62, v62, v62 quad_perm:[2,3,0,1] row_mask:0xf bank_mask:0xf bound_ctrl:1
	v_pk_fma_f32 v[92:93], v[142:143], v[136:137], v[92:93] op_sel_hi:[0,1,1]
	v_add_f32_dpp v60, v60, v60 row_half_mirror row_mask:0xf bank_mask:0xf bound_ctrl:1
	v_add_f32_dpp v62, v62, v62 row_half_mirror row_mask:0xf bank_mask:0xf bound_ctrl:1
	ds_read_b128 v[126:129], v74 offset:45568
	v_add_f32_dpp v60, v60, v60 row_mirror row_mask:0xf bank_mask:0xf bound_ctrl:1
	v_add_f32_dpp v62, v62, v62 row_mirror row_mask:0xf bank_mask:0xf bound_ctrl:1
	ds_read_b128 v[134:137], v74 offset:46080
	ds_read_b32 v142, v75 offset:46592
	v_pk_fma_f32 v[94:95], v[130:131], v[60:61], v[94:95] op_sel_hi:[1,0,1] neg_lo:[1,0,0] neg_hi:[1,0,0]
	v_pk_fma_f32 v[92:93], v[132:133], v[60:61], v[92:93] op_sel_hi:[1,0,1] neg_lo:[1,0,0] neg_hi:[1,0,0]
	v_pk_mul_f32 v[238:239], v[130:131], v[62:63] op_sel_hi:[1,0]
	v_pk_mul_f32 v[240:241], v[132:133], v[62:63] op_sel_hi:[1,0]
	ds_read_b128 v[130:133], v74 offset:45824
	v_pk_mul_f32 v[64:65], v[138:139], v[94:95]
	v_pk_fma_f32 v[88:89], v[88:89], v[122:123], v[238:239] neg_lo:[0,0,1] neg_hi:[0,0,1]
	v_pk_fma_f32 v[90:91], v[90:91], v[124:125], v[240:241] neg_lo:[0,0,1] neg_hi:[0,0,1]
	ds_read_b128 v[122:125], v74 offset:45312
	v_pk_fma_f32 v[64:65], v[140:141], v[92:93], v[64:65]
	v_pk_mul_f32 v[66:67], v[138:139], v[88:89]
	v_pk_fma_f32 v[66:67], v[140:141], v[90:91], v[66:67]
	ds_read_b128 v[138:141], v74 offset:46336
	v_add_f32_e32 v155, v64, v65
	v_add_f32_e32 v176, v66, v67
	s_waitcnt lgkmcnt(6)
	v_pk_mul_f32 v[60:61], v[94:95], v[220:221]
	v_pk_mul_f32 v[62:63], v[88:89], v[220:221]
	v_pk_fma_f32 v[60:61], v[92:93], v[222:223], v[60:61]
	v_pk_fma_f32 v[62:63], v[90:91], v[222:223], v[62:63]
	v_add_f32_e32 v60, v60, v61
	v_add_f32_e32 v62, v62, v63
	v_pk_mul_f32 v[94:95], v[94:95], v[216:217]
	v_pk_mul_f32 v[92:93], v[92:93], v[218:219]
	v_add_f32_dpp v60, v60, v60 quad_perm:[1,0,3,2] row_mask:0xf bank_mask:0xf bound_ctrl:1
	v_add_f32_dpp v62, v62, v62 quad_perm:[1,0,3,2] row_mask:0xf bank_mask:0xf bound_ctrl:1
	v_pk_fma_f32 v[94:95], v[236:237], v[228:229], v[94:95] op_sel_hi:[0,1,1]
	v_add_f32_dpp v60, v60, v60 quad_perm:[2,3,0,1] row_mask:0xf bank_mask:0xf bound_ctrl:1
	v_add_f32_dpp v62, v62, v62 quad_perm:[2,3,0,1] row_mask:0xf bank_mask:0xf bound_ctrl:1
	v_pk_fma_f32 v[92:93], v[236:237], v[230:231], v[92:93] op_sel_hi:[0,1,1]
	v_add_f32_dpp v60, v60, v60 row_half_mirror row_mask:0xf bank_mask:0xf bound_ctrl:1
	v_add_f32_dpp v62, v62, v62 row_half_mirror row_mask:0xf bank_mask:0xf bound_ctrl:1
	ds_read_b128 v[220:223], v74 offset:47104
	v_add_f32_dpp v60, v60, v60 row_mirror row_mask:0xf bank_mask:0xf bound_ctrl:1
	v_add_f32_dpp v62, v62, v62 row_mirror row_mask:0xf bank_mask:0xf bound_ctrl:1
	ds_read_b128 v[228:231], v74 offset:47616
	ds_read_b32 v236, v75 offset:48128
	v_pk_fma_f32 v[94:95], v[224:225], v[60:61], v[94:95] op_sel_hi:[1,0,1] neg_lo:[1,0,0] neg_hi:[1,0,0]
	v_pk_fma_f32 v[92:93], v[226:227], v[60:61], v[92:93] op_sel_hi:[1,0,1] neg_lo:[1,0,0] neg_hi:[1,0,0]
	v_pk_mul_f32 v[238:239], v[224:225], v[62:63] op_sel_hi:[1,0]
	v_pk_mul_f32 v[240:241], v[226:227], v[62:63] op_sel_hi:[1,0]
	ds_read_b128 v[224:227], v74 offset:47360
	v_pk_mul_f32 v[64:65], v[232:233], v[94:95]
	v_pk_fma_f32 v[88:89], v[88:89], v[216:217], v[238:239] neg_lo:[0,0,1] neg_hi:[0,0,1]
	v_pk_fma_f32 v[90:91], v[90:91], v[218:219], v[240:241] neg_lo:[0,0,1] neg_hi:[0,0,1]
	ds_read_b128 v[216:219], v74 offset:46848
	v_pk_fma_f32 v[64:65], v[234:235], v[92:93], v[64:65]
	v_pk_mul_f32 v[66:67], v[232:233], v[88:89]
	v_pk_fma_f32 v[66:67], v[234:235], v[90:91], v[66:67]
	ds_read_b128 v[232:235], v74 offset:47872
	v_add_f32_e32 v156, v64, v65
	v_add_f32_e32 v177, v66, v67
	s_waitcnt lgkmcnt(6)
	v_pk_mul_f32 v[60:61], v[94:95], v[126:127]
	v_pk_mul_f32 v[62:63], v[88:89], v[126:127]
	v_pk_fma_f32 v[60:61], v[92:93], v[128:129], v[60:61]
	v_pk_fma_f32 v[62:63], v[90:91], v[128:129], v[62:63]
	v_add_f32_e32 v60, v60, v61
	v_add_f32_e32 v62, v62, v63
	v_pk_mul_f32 v[94:95], v[94:95], v[122:123]
	v_pk_mul_f32 v[92:93], v[92:93], v[124:125]
	v_add_f32_dpp v60, v60, v60 quad_perm:[1,0,3,2] row_mask:0xf bank_mask:0xf bound_ctrl:1
	v_add_f32_dpp v62, v62, v62 quad_perm:[1,0,3,2] row_mask:0xf bank_mask:0xf bound_ctrl:1
	v_pk_fma_f32 v[94:95], v[142:143], v[134:135], v[94:95] op_sel_hi:[0,1,1]
	v_add_f32_dpp v60, v60, v60 quad_perm:[2,3,0,1] row_mask:0xf bank_mask:0xf bound_ctrl:1
	v_add_f32_dpp v62, v62, v62 quad_perm:[2,3,0,1] row_mask:0xf bank_mask:0xf bound_ctrl:1
	v_pk_fma_f32 v[92:93], v[142:143], v[136:137], v[92:93] op_sel_hi:[0,1,1]
	v_add_f32_dpp v60, v60, v60 row_half_mirror row_mask:0xf bank_mask:0xf bound_ctrl:1
	v_add_f32_dpp v62, v62, v62 row_half_mirror row_mask:0xf bank_mask:0xf bound_ctrl:1
	ds_read_b128 v[126:129], v74 offset:48640
	v_add_f32_dpp v60, v60, v60 row_mirror row_mask:0xf bank_mask:0xf bound_ctrl:1
	v_add_f32_dpp v62, v62, v62 row_mirror row_mask:0xf bank_mask:0xf bound_ctrl:1
	ds_read_b128 v[134:137], v74 offset:49152
	ds_read_b32 v142, v75 offset:49664
	v_pk_fma_f32 v[94:95], v[130:131], v[60:61], v[94:95] op_sel_hi:[1,0,1] neg_lo:[1,0,0] neg_hi:[1,0,0]
	v_pk_fma_f32 v[92:93], v[132:133], v[60:61], v[92:93] op_sel_hi:[1,0,1] neg_lo:[1,0,0] neg_hi:[1,0,0]
	v_pk_mul_f32 v[238:239], v[130:131], v[62:63] op_sel_hi:[1,0]
	v_pk_mul_f32 v[240:241], v[132:133], v[62:63] op_sel_hi:[1,0]
	ds_read_b128 v[130:133], v74 offset:48896
	v_pk_mul_f32 v[64:65], v[138:139], v[94:95]
	v_pk_fma_f32 v[88:89], v[88:89], v[122:123], v[238:239] neg_lo:[0,0,1] neg_hi:[0,0,1]
	v_pk_fma_f32 v[90:91], v[90:91], v[124:125], v[240:241] neg_lo:[0,0,1] neg_hi:[0,0,1]
	ds_read_b128 v[122:125], v74 offset:48384
	v_pk_fma_f32 v[64:65], v[140:141], v[92:93], v[64:65]
	v_pk_mul_f32 v[66:67], v[138:139], v[88:89]
	v_pk_fma_f32 v[66:67], v[140:141], v[90:91], v[66:67]
	ds_read_b128 v[138:141], v74 offset:49408
	v_add_f32_e32 v157, v64, v65
	v_add_f32_e32 v178, v66, v67
	s_waitcnt lgkmcnt(6)
; template <bool DUAL>
; __device__ __forceinline__ void rwkv_tile(const Params& p, int l, int tile, unsigned char* smem) {
;     ...
; #pragma unroll 2
;       for (int i = 0; i < 32; ++i) {
;         const int inx = (i + 1) & 31;
;         const float4 nw4 = *(const float4*)(rp + inx * 384), nkk4 = *(const float4*)(rp + inx * 384 + 64), nkb4 = *(const float4*)(rp + inx * 384 + 128);
;         const float4 nkd4 = *(const float4*)(rp + inx * 384 + 192), nr4 = *(const float4*)(rp + inx * 384 + 256);
;         const float nv = vp[inx * 384];
;         v2f t = sA * (v2f){kk4.x, kk4.y};
;         t = sB * (v2f){kk4.z, kk4.w} + t;
;         float sa = t.x + t.y, ia = 0.f;
;         if (DUAL) {
;           v2f ti = iA * (v2f){kk4.x, kk4.y};
;           ti = iB * (v2f){kk4.z, kk4.w} + ti;
;           ia = ti.x + ti.y;
;           sa += dppf<0xB1>(sa); ia += dppf<0xB1>(ia);
;           sa += dppf<0x4E>(sa); ia += dppf<0x4E>(ia);
;           sa += dppf<0x141>(sa); ia += dppf<0x141>(ia);
;           sa += dppf<0x140>(sa); ia += dppf<0x140>(ia);
;         } else {
;           sa = sum16(sa);
;         }
;         v2f cA = sA * (v2f){w4.x, w4.y} + (v2f){kd4.x, kd4.y} * v;
;         v2f cB = sB * (v2f){w4.z, w4.w} + (v2f){kd4.z, kd4.w} * v;
;         sA = cA - (v2f){kb4.x, kb4.y} * sa;
;         sB = cB - (v2f){kb4.z, kb4.w} * sa;
;         v2f u = sA * (v2f){r4.x, r4.y};
;         u = sB * (v2f){r4.z, r4.w} + u;
;         float y = u.x + u.y, g = 0.f;
;         if (DUAL) {
;           iA = iA * (v2f){w4.x, w4.y} - (v2f){kb4.x, kb4.y} * ia;
;           iB = iB * (v2f){w4.z, w4.w} - (v2f){kb4.z, kb4.w} * ia;
;           v2f ui = iA * (v2f){r4.x, r4.y};
;           ui = iB * (v2f){r4.z, r4.w} + ui;
;           g = ui.x + ui.y;
;           y += dppf<0xB1>(y); g += dppf<0xB1>(g);
;           y += dppf<0x4E>(y); g += dppf<0x4E>(g);
;           y += dppf<0x141>(y); g += dppf<0x141>(g);
;           y += dppf<0x140>(y); g += dppf<0x140>(g);
;           if (fr == (i & 15)) gkeep = g;
;         } else {
;           y = sum16(y);
;         }
;         if (fr == (i & 15)) ykeep = y;
	v_pk_mul_f32 v[60:61], v[94:95], v[220:221]
	v_pk_mul_f32 v[62:63], v[88:89], v[220:221]
	v_pk_fma_f32 v[60:61], v[92:93], v[222:223], v[60:61]
	v_pk_fma_f32 v[62:63], v[90:91], v[222:223], v[62:63]
	v_add_f32_e32 v60, v60, v61
	v_add_f32_e32 v62, v62, v63
	v_pk_mul_f32 v[94:95], v[94:95], v[216:217]
	v_pk_mul_f32 v[92:93], v[92:93], v[218:219]
	v_add_f32_dpp v60, v60, v60 quad_perm:[1,0,3,2] row_mask:0xf bank_mask:0xf bound_ctrl:1
	v_add_f32_dpp v62, v62, v62 quad_perm:[1,0,3,2] row_mask:0xf bank_mask:0xf bound_ctrl:1
	v_pk_fma_f32 v[94:95], v[236:237], v[228:229], v[94:95] op_sel_hi:[0,1,1]
	v_add_f32_dpp v60, v60, v60 quad_perm:[2,3,0,1] row_mask:0xf bank_mask:0xf bound_ctrl:1
	v_add_f32_dpp v62, v62, v62 quad_perm:[2,3,0,1] row_mask:0xf bank_mask:0xf bound_ctrl:1
	v_pk_fma_f32 v[92:93], v[236:237], v[230:231], v[92:93] op_sel_hi:[0,1,1]
	v_add_f32_dpp v60, v60, v60 row_half_mirror row_mask:0xf bank_mask:0xf bound_ctrl:1
	v_add_f32_dpp v62, v62, v62 row_half_mirror row_mask:0xf bank_mask:0xf bound_ctrl:1
	ds_read_b128 v[220:223], v69 offset:25600
	v_add_f32_dpp v60, v60, v60 row_mirror row_mask:0xf bank_mask:0xf bound_ctrl:1
	v_add_f32_dpp v62, v62, v62 row_mirror row_mask:0xf bank_mask:0xf bound_ctrl:1
	ds_read_b128 v[228:231], v69 offset:26112
	ds_read_b32 v236, v70 offset:26624
	v_pk_fma_f32 v[94:95], v[224:225], v[60:61], v[94:95] op_sel_hi:[1,0,1] neg_lo:[1,0,0] neg_hi:[1,0,0]
	v_pk_fma_f32 v[92:93], v[226:227], v[60:61], v[92:93] op_sel_hi:[1,0,1] neg_lo:[1,0,0] neg_hi:[1,0,0]
	v_pk_mul_f32 v[238:239], v[224:225], v[62:63] op_sel_hi:[1,0]
	v_pk_mul_f32 v[240:241], v[226:227], v[62:63] op_sel_hi:[1,0]
	ds_read_b128 v[224:227], v69 offset:25856
	v_pk_mul_f32 v[64:65], v[232:233], v[94:95]
	v_pk_fma_f32 v[88:89], v[88:89], v[216:217], v[238:239] neg_lo:[0,0,1] neg_hi:[0,0,1]
	v_pk_fma_f32 v[90:91], v[90:91], v[218:219], v[240:241] neg_lo:[0,0,1] neg_hi:[0,0,1]
	ds_read_b128 v[216:219], v69 offset:25344
	v_pk_fma_f32 v[64:65], v[234:235], v[92:93], v[64:65]
	v_pk_mul_f32 v[66:67], v[232:233], v[88:89]
	v_pk_fma_f32 v[66:67], v[234:235], v[90:91], v[66:67]
	ds_read_b128 v[232:235], v69 offset:26368
	v_add_f32_e32 v158, v64, v65
	v_add_f32_e32 v179, v66, v67
	s_waitcnt lgkmcnt(6)
	v_pk_mul_f32 v[60:61], v[94:95], v[126:127]
	v_pk_mul_f32 v[62:63], v[88:89], v[126:127]
	v_pk_fma_f32 v[60:61], v[92:93], v[128:129], v[60:61]
	v_pk_fma_f32 v[62:63], v[90:91], v[128:129], v[62:63]
	v_add_f32_e32 v60, v60, v61
	v_add_f32_e32 v62, v62, v63
	v_pk_mul_f32 v[94:95], v[94:95], v[122:123]
	v_pk_mul_f32 v[92:93], v[92:93], v[124:125]
	v_add_f32_dpp v60, v60, v60 quad_perm:[1,0,3,2] row_mask:0xf bank_mask:0xf bound_ctrl:1
	v_add_f32_dpp v62, v62, v62 quad_perm:[1,0,3,2] row_mask:0xf bank_mask:0xf bound_ctrl:1
	v_pk_fma_f32 v[94:95], v[142:143], v[134:135], v[94:95] op_sel_hi:[0,1,1]
	v_add_f32_dpp v60, v60, v60 quad_perm:[2,3,0,1] row_mask:0xf bank_mask:0xf bound_ctrl:1
	v_add_f32_dpp v62, v62, v62 quad_perm:[2,3,0,1] row_mask:0xf bank_mask:0xf bound_ctrl:1
	v_pk_fma_f32 v[92:93], v[142:143], v[136:137], v[92:93] op_sel_hi:[0,1,1]
	v_add_f32_dpp v60, v60, v60 row_half_mirror row_mask:0xf bank_mask:0xf bound_ctrl:1
	v_add_f32_dpp v62, v62, v62 row_half_mirror row_mask:0xf bank_mask:0xf bound_ctrl:1
	ds_read_b128 v[126:129], v69 offset:27136
	v_add_f32_dpp v60, v60, v60 row_mirror row_mask:0xf bank_mask:0xf bound_ctrl:1
	v_add_f32_dpp v62, v62, v62 row_mirror row_mask:0xf bank_mask:0xf bound_ctrl:1
	ds_read_b128 v[134:137], v69 offset:27648
	ds_read_b32 v142, v70 offset:28160
	v_pk_fma_f32 v[94:95], v[130:131], v[60:61], v[94:95] op_sel_hi:[1,0,1] neg_lo:[1,0,0] neg_hi:[1,0,0]
	v_pk_fma_f32 v[92:93], v[132:133], v[60:61], v[92:93] op_sel_hi:[1,0,1] neg_lo:[1,0,0] neg_hi:[1,0,0]
	v_pk_mul_f32 v[238:239], v[130:131], v[62:63] op_sel_hi:[1,0]
	v_pk_mul_f32 v[240:241], v[132:133], v[62:63] op_sel_hi:[1,0]
	ds_read_b128 v[130:133], v69 offset:27392
	v_pk_mul_f32 v[64:65], v[138:139], v[94:95]
	v_pk_fma_f32 v[88:89], v[88:89], v[122:123], v[238:239] neg_lo:[0,0,1] neg_hi:[0,0,1]
	v_pk_fma_f32 v[90:91], v[90:91], v[124:125], v[240:241] neg_lo:[0,0,1] neg_hi:[0,0,1]
	ds_read_b128 v[122:125], v69 offset:26880
	v_pk_fma_f32 v[64:65], v[140:141], v[92:93], v[64:65]
	v_pk_mul_f32 v[66:67], v[138:139], v[88:89]
	v_pk_fma_f32 v[66:67], v[140:141], v[90:91], v[66:67]
	ds_read_b128 v[138:141], v69 offset:27904
	v_add_f32_e32 v159, v64, v65
	v_add_f32_e32 v180, v66, v67
	v_add_f32_dpp v144, v144, v144 row_shl:8 row_mask:0xf bank_mask:0x3
	v_add_f32_dpp v144, v152, v152 row_shr:8 row_mask:0xf bank_mask:0xc
	v_add_f32_dpp v145, v145, v145 row_shl:8 row_mask:0xf bank_mask:0x3
	v_add_f32_dpp v145, v153, v153 row_shr:8 row_mask:0xf bank_mask:0xc
	v_add_f32_dpp v146, v146, v146 row_shl:8 row_mask:0xf bank_mask:0x3
	v_add_f32_dpp v146, v154, v154 row_shr:8 row_mask:0xf bank_mask:0xc
	v_add_f32_dpp v147, v147, v147 row_shl:8 row_mask:0xf bank_mask:0x3
	v_add_f32_dpp v147, v155, v155 row_shr:8 row_mask:0xf bank_mask:0xc
	v_add_f32_dpp v148, v148, v148 row_shl:8 row_mask:0xf bank_mask:0x3
	v_add_f32_dpp v148, v156, v156 row_shr:8 row_mask:0xf bank_mask:0xc
	v_add_f32_dpp v149, v149, v149 row_shl:8 row_mask:0xf bank_mask:0x3
	v_add_f32_dpp v149, v157, v157 row_shr:8 row_mask:0xf bank_mask:0xc
	v_add_f32_dpp v150, v150, v150 row_shl:8 row_mask:0xf bank_mask:0x3
	v_add_f32_dpp v150, v158, v158 row_shr:8 row_mask:0xf bank_mask:0xc
	v_add_f32_dpp v151, v151, v151 row_shl:8 row_mask:0xf bank_mask:0x3
	v_add_f32_dpp v151, v159, v159 row_shr:8 row_mask:0xf bank_mask:0xc
	v_add_f32_dpp v144, v144, v144 row_shl:4 row_mask:0xf bank_mask:0x5
	v_add_f32_dpp v144, v148, v148 row_shr:4 row_mask:0xf bank_mask:0xa
; __device__ __forceinline__ bf16_t f2bf(float f) { return (bf16_t)(pack2(f, 0.f) & 0xffffu); }
; template <bool DUAL>
; __device__ __forceinline__ void rwkv_tile(const Params& p, int l, int tile, unsigned char* smem) {
;     ...
;           sa = sum16(sa);
;         }
;         v2f cA = sA * (v2f){w4.x, w4.y} + (v2f){kd4.x, kd4.y} * v;
;         v2f cB = sB * (v2f){w4.z, w4.w} + (v2f){kd4.z, kd4.w} * v;
;         sA = cA - (v2f){kb4.x, kb4.y} * sa;
;         sB = cB - (v2f){kb4.z, kb4.w} * sa;
;         v2f u = sA * (v2f){r4.x, r4.y};
;         u = sB * (v2f){r4.z, r4.w} + u;
;         float y = u.x + u.y, g = 0.f;
;         if (DUAL) {
;           iA = iA * (v2f){w4.x, w4.y} - (v2f){kb4.x, kb4.y} * ia;
;           iB = iB * (v2f){w4.z, w4.w} - (v2f){kb4.z, kb4.w} * ia;
;           v2f ui = iA * (v2f){r4.x, r4.y};
;           ui = iB * (v2f){r4.z, r4.w} + ui;
;           g = ui.x + ui.y;
;           y += dppf<0xB1>(y); g += dppf<0xB1>(g);
;           y += dppf<0x4E>(y); g += dppf<0x4E>(g);
;           y += dppf<0x141>(y); g += dppf<0x141>(g);
;           y += dppf<0x140>(y); g += dppf<0x140>(g);
;           if (fr == (i & 15)) gkeep = g;
;         } else {
;           y = sum16(y);
;         }
;         if (fr == (i & 15)) ykeep = y;
;         if ((i & 15) == 15) {
;           const int ii = (i & 16) + fr;
;           const int ri = (d == 0) ? ii + 1 : 32 - ii;
;           const int pi = plo - 1 + ri;
;           p.yR[((size_t)d * TOK + rowbase + pi) * 256 + h * 64 + row] = f2bf(ykeep);
;           if (DUAL) p.GID[((size_t)(d * 4 + b) * NSEG1 + (cix - CSPLIT) * 32 + ii) * 256 + h * 64 + row] = f2bf(gkeep);
;         }
;         w4 = nw4; kk4 = nkk4; kb4 = nkb4; kd4 = nkd4; r4 = nr4; v = nv;
	v_add_f32_dpp v145, v145, v145 row_shl:4 row_mask:0xf bank_mask:0x5
	v_add_f32_dpp v145, v149, v149 row_shr:4 row_mask:0xf bank_mask:0xa
	v_add_f32_dpp v146, v146, v146 row_shl:4 row_mask:0xf bank_mask:0x5
	v_add_f32_dpp v146, v150, v150 row_shr:4 row_mask:0xf bank_mask:0xa
	v_add_f32_dpp v147, v147, v147 row_shl:4 row_mask:0xf bank_mask:0x5
	v_add_f32_dpp v147, v151, v151 row_shr:4 row_mask:0xf bank_mask:0xa
	v_cndmask_b32_e32 v160, v144, v146, vcc
	v_cndmask_b32_e32 v161, v146, v144, vcc
	v_cndmask_b32_e32 v163, v147, v145, vcc
	v_cndmask_b32_e32 v162, v145, v147, vcc
	v_add_f32_dpp v160, v161, v160 quad_perm:[2,3,0,1] row_mask:0xf bank_mask:0xf
	v_add_f32_dpp v162, v163, v162 quad_perm:[2,3,0,1] row_mask:0xf bank_mask:0xf
	v_cndmask_b32_e64 v181, v160, v162, s[58:59]
	v_cndmask_b32_e64 v182, v162, v160, s[58:59]
	v_add_u32_e32 v74, 0x6000, v74
	v_add_u32_e32 v75, 0x6000, v75
	v_add_f32_dpp v72, v182, v181 quad_perm:[1,0,3,2] row_mask:0xf bank_mask:0xf
	v_add_f32_dpp v165, v165, v165 row_shl:8 row_mask:0xf bank_mask:0x3
	v_add_f32_dpp v165, v173, v173 row_shr:8 row_mask:0xf bank_mask:0xc
	v_add_f32_dpp v166, v166, v166 row_shl:8 row_mask:0xf bank_mask:0x3
	v_add_f32_dpp v166, v174, v174 row_shr:8 row_mask:0xf bank_mask:0xc
	v_add_f32_dpp v167, v167, v167 row_shl:8 row_mask:0xf bank_mask:0x3
	v_add_f32_dpp v167, v175, v175 row_shr:8 row_mask:0xf bank_mask:0xc
	v_add_f32_dpp v168, v168, v168 row_shl:8 row_mask:0xf bank_mask:0x3
	v_add_f32_dpp v168, v176, v176 row_shr:8 row_mask:0xf bank_mask:0xc
	v_add_f32_dpp v169, v169, v169 row_shl:8 row_mask:0xf bank_mask:0x3
	v_add_f32_dpp v169, v177, v177 row_shr:8 row_mask:0xf bank_mask:0xc
	v_add_f32_dpp v170, v170, v170 row_shl:8 row_mask:0xf bank_mask:0x3
	v_add_f32_dpp v170, v178, v178 row_shr:8 row_mask:0xf bank_mask:0xc
	v_add_f32_dpp v171, v171, v171 row_shl:8 row_mask:0xf bank_mask:0x3
	v_add_f32_dpp v171, v179, v179 row_shr:8 row_mask:0xf bank_mask:0xc
	v_add_f32_dpp v172, v172, v172 row_shl:8 row_mask:0xf bank_mask:0x3
	v_add_f32_dpp v172, v180, v180 row_shr:8 row_mask:0xf bank_mask:0xc
	v_add_f32_dpp v165, v165, v165 row_shl:4 row_mask:0xf bank_mask:0x5
	v_add_f32_dpp v165, v169, v169 row_shr:4 row_mask:0xf bank_mask:0xa
	v_add_f32_dpp v166, v166, v166 row_shl:4 row_mask:0xf bank_mask:0x5
	v_add_f32_dpp v166, v170, v170 row_shr:4 row_mask:0xf bank_mask:0xa
	v_add_f32_dpp v167, v167, v167 row_shl:4 row_mask:0xf bank_mask:0x5
	v_add_f32_dpp v167, v171, v171 row_shr:4 row_mask:0xf bank_mask:0xa
	v_add_f32_dpp v168, v168, v168 row_shl:4 row_mask:0xf bank_mask:0x5
	v_add_f32_dpp v168, v172, v172 row_shr:4 row_mask:0xf bank_mask:0xa
	v_cndmask_b32_e32 v160, v165, v167, vcc
	v_cndmask_b32_e32 v161, v167, v165, vcc
	v_cndmask_b32_e32 v163, v168, v166, vcc
	v_cndmask_b32_e32 v162, v166, v168, vcc
	v_add_f32_dpp v160, v161, v160 quad_perm:[2,3,0,1] row_mask:0xf bank_mask:0xf
	v_add_f32_dpp v162, v163, v162 quad_perm:[2,3,0,1] row_mask:0xf bank_mask:0xf
	v_cndmask_b32_e64 v181, v160, v162, s[58:59]
	v_cndmask_b32_e64 v182, v162, v160, s[58:59]
	v_mov_b32_e32 v69, v102
	v_mov_b32_e32 v70, v103
	v_add_f32_dpp v73, v182, v181 quad_perm:[1,0,3,2] row_mask:0xf bank_mask:0xf
	v_mov_b32_e32 v79, v68
	v_add_u32_e32 v77, 1, v79
	v_sub_u32_e32 v76, 32, v79
	v_cndmask_b32_e64 v76, v76, v77, s[36:37]
	v_add_u32_e32 v76, s28, v76
	v_ashrrev_i32_e32 v77, 31, v76
	v_lshl_add_u64 v[76:77], s[20:21], 0, v[76:77]
	v_lshlrev_b64 v[76:77], 9, v[76:77]
	v_cvt_pk_bf16_f32 v78, v72, v72
	v_lshl_add_u64 v[76:77], v[84:85], 0, v[76:77]
	global_store_short v[76:77], v78, off
	v_or_b32_e32 v76, s53, v79
	v_mov_b32_e32 v77, s54
	v_cvt_pk_bf16_f32 v79, v73, v73
	v_lshlrev_b64 v[76:77], 9, v[76:77]
	v_lshl_add_u64 v[76:77], v[86:87], 0, v[76:77]
	global_store_short v[76:77], v79, off
	v_add_u32_e32 v68, 16, v68
	s_add_i32 s55, s55, 1
	s_cmp_lg_u32 s55, 2
	s_cbranch_scc1 .Lrw_du_loop
	s_branch .LBB0_1436
.Lrw_nd_scan:
	v_mov_b32_e32 v72, v99
	v_mov_b32_e32 v73, v100
	v_add_u32_e32 v68, 0x6000, v99
	v_add_u32_e32 v69, 0x6000, v100
	v_mov_b32_e32 v71, v98
	s_mov_b32 vcc_lo, 0xcccccccc
	s_mov_b32 vcc_hi, 0xcccccccc
	s_mov_b32 s58, 0xaaaaaaaa
	s_mov_b32 s59, 0xaaaaaaaa
	ds_read_b128 v[220:223], v72 offset:25600
	ds_read_b128 v[216:219], v72 offset:25344
	ds_read_b128 v[228:231], v72 offset:26112
	ds_read_b32 v236, v73 offset:26624
	ds_read_b128 v[224:227], v72 offset:25856
	ds_read_b128 v[232:235], v72 offset:26368
	ds_read_b128 v[122:125], v72 offset:27136
	ds_read_b128 v[118:121], v72 offset:26880
	ds_read_b128 v[130:133], v72 offset:27648
	ds_read_b32 v138, v73 offset:28160
	ds_read_b128 v[126:129], v72 offset:27392
	ds_read_b128 v[134:137], v72 offset:27904
	s_mov_b32 s50, 0
; template <bool DUAL>
; __device__ __forceinline__ void rwkv_tile(const Params& p, int l, int tile, unsigned char* smem) {
;     ...
; #pragma unroll 2
;       for (int i = 0; i < 32; ++i) {
;         const int inx = (i + 1) & 31;
;         const float4 nw4 = *(const float4*)(rp + inx * 384), nkk4 = *(const float4*)(rp + inx * 384 + 64), nkb4 = *(const float4*)(rp + inx * 384 + 128);
;         const float4 nkd4 = *(const float4*)(rp + inx * 384 + 192), nr4 = *(const float4*)(rp + inx * 384 + 256);
;         const float nv = vp[inx * 384];
;         v2f t = sA * (v2f){kk4.x, kk4.y};
;         t = sB * (v2f){kk4.z, kk4.w} + t;
;         float sa = t.x + t.y, ia = 0.f;
;         if (DUAL) {
;           v2f ti = iA * (v2f){kk4.x, kk4.y};
;           ti = iB * (v2f){kk4.z, kk4.w} + ti;
;           ia = ti.x + ti.y;
;           sa += dppf<0xB1>(sa); ia += dppf<0xB1>(ia);
;           sa += dppf<0x4E>(sa); ia += dppf<0x4E>(ia);
;           sa += dppf<0x141>(sa); ia += dppf<0x141>(ia);
;           sa += dppf<0x140>(sa); ia += dppf<0x140>(ia);
;         } else {
;           sa = sum16(sa);
;         }
;         v2f cA = sA * (v2f){w4.x, w4.y} + (v2f){kd4.x, kd4.y} * v;
;         v2f cB = sB * (v2f){w4.z, w4.w} + (v2f){kd4.z, kd4.w} * v;
;         sA = cA - (v2f){kb4.x, kb4.y} * sa;
;         sB = cB - (v2f){kb4.z, kb4.w} * sa;
;         v2f u = sA * (v2f){r4.x, r4.y};
;         u = sB * (v2f){r4.z, r4.w} + u;
;         float y = u.x + u.y, g = 0.f;
;         if (DUAL) {
;           iA = iA * (v2f){w4.x, w4.y} - (v2f){kb4.x, kb4.y} * ia;
;           iB = iB * (v2f){w4.z, w4.w} - (v2f){kb4.z, kb4.w} * ia;
;           v2f ui = iA * (v2f){r4.x, r4.y};
;           ui = iB * (v2f){r4.z, r4.w} + ui;
;           g = ui.x + ui.y;
;           y += dppf<0xB1>(y); g += dppf<0xB1>(g);
;           y += dppf<0x4E>(y); g += dppf<0x4E>(g);
;           y += dppf<0x141>(y); g += dppf<0x141>(g);
;           y += dppf<0x140>(y); g += dppf<0x140>(g);
;           if (fr == (i & 15)) gkeep = g;
;         } else {
;           y = sum16(y);
;         }
;         if (fr == (i & 15)) ykeep = y;
.Lrw_nd_loop:
	s_waitcnt lgkmcnt(6)
	v_pk_mul_f32 v[64:65], v[60:61], v[220:221]
	v_pk_fma_f32 v[64:65], v[62:63], v[222:223], v[64:65]
	v_add_f32_e32 v64, v64, v65
	v_pk_mul_f32 v[60:61], v[60:61], v[216:217]
	v_pk_mul_f32 v[62:63], v[62:63], v[218:219]
	v_add_f32_dpp v64, v64, v64 quad_perm:[1,0,3,2] row_mask:0xf bank_mask:0xf bound_ctrl:1
	v_pk_fma_f32 v[60:61], v[236:237], v[228:229], v[60:61] op_sel_hi:[0,1,1]
	v_pk_fma_f32 v[62:63], v[236:237], v[230:231], v[62:63] op_sel_hi:[0,1,1]
	v_add_f32_dpp v64, v64, v64 quad_perm:[2,3,0,1] row_mask:0xf bank_mask:0xf bound_ctrl:1
	ds_read_b128 v[220:223], v72 offset:28672
	ds_read_b128 v[216:219], v72 offset:28416
	v_add_f32_dpp v64, v64, v64 row_half_mirror row_mask:0xf bank_mask:0xf bound_ctrl:1
	ds_read_b128 v[228:231], v72 offset:29184
	ds_read_b32 v236, v73 offset:29696
	v_add_f32_dpp v64, v64, v64 row_mirror row_mask:0xf bank_mask:0xf bound_ctrl:1
	v_pk_fma_f32 v[60:61], v[224:225], v[64:65], v[60:61] op_sel_hi:[1,0,1] neg_lo:[1,0,0] neg_hi:[1,0,0]
	v_pk_fma_f32 v[62:63], v[226:227], v[64:65], v[62:63] op_sel_hi:[1,0,1] neg_lo:[1,0,0] neg_hi:[1,0,0]
	ds_read_b128 v[224:227], v72 offset:28928
	v_pk_mul_f32 v[66:67], v[232:233], v[60:61]
	v_pk_fma_f32 v[66:67], v[234:235], v[62:63], v[66:67]
	ds_read_b128 v[232:235], v72 offset:29440
	v_add_f32_e32 v140, v66, v67
	s_waitcnt lgkmcnt(6)
	v_pk_mul_f32 v[64:65], v[60:61], v[122:123]
	v_pk_fma_f32 v[64:65], v[62:63], v[124:125], v[64:65]
	v_add_f32_e32 v64, v64, v65
	v_pk_mul_f32 v[60:61], v[60:61], v[118:119]
	v_pk_mul_f32 v[62:63], v[62:63], v[120:121]
	v_add_f32_dpp v64, v64, v64 quad_perm:[1,0,3,2] row_mask:0xf bank_mask:0xf bound_ctrl:1
	v_pk_fma_f32 v[60:61], v[138:139], v[130:131], v[60:61] op_sel_hi:[0,1,1]
	v_pk_fma_f32 v[62:63], v[138:139], v[132:133], v[62:63] op_sel_hi:[0,1,1]
	v_add_f32_dpp v64, v64, v64 quad_perm:[2,3,0,1] row_mask:0xf bank_mask:0xf bound_ctrl:1
	ds_read_b128 v[122:125], v72 offset:30208
	ds_read_b128 v[118:121], v72 offset:29952
	v_add_f32_dpp v64, v64, v64 row_half_mirror row_mask:0xf bank_mask:0xf bound_ctrl:1
	ds_read_b128 v[130:133], v72 offset:30720
	ds_read_b32 v138, v73 offset:31232
	v_add_f32_dpp v64, v64, v64 row_mirror row_mask:0xf bank_mask:0xf bound_ctrl:1
	v_pk_fma_f32 v[60:61], v[126:127], v[64:65], v[60:61] op_sel_hi:[1,0,1] neg_lo:[1,0,0] neg_hi:[1,0,0]
	v_pk_fma_f32 v[62:63], v[128:129], v[64:65], v[62:63] op_sel_hi:[1,0,1] neg_lo:[1,0,0] neg_hi:[1,0,0]
	ds_read_b128 v[126:129], v72 offset:30464
	v_pk_mul_f32 v[66:67], v[134:135], v[60:61]
	v_pk_fma_f32 v[66:67], v[136:137], v[62:63], v[66:67]
	ds_read_b128 v[134:137], v72 offset:30976
	v_add_f32_e32 v141, v66, v67
	s_waitcnt lgkmcnt(6)
	v_pk_mul_f32 v[64:65], v[60:61], v[220:221]
	v_pk_fma_f32 v[64:65], v[62:63], v[222:223], v[64:65]
	v_add_f32_e32 v64, v64, v65
	v_pk_mul_f32 v[60:61], v[60:61], v[216:217]
	v_pk_mul_f32 v[62:63], v[62:63], v[218:219]
	v_add_f32_dpp v64, v64, v64 quad_perm:[1,0,3,2] row_mask:0xf bank_mask:0xf bound_ctrl:1
	v_pk_fma_f32 v[60:61], v[236:237], v[228:229], v[60:61] op_sel_hi:[0,1,1]
	v_pk_fma_f32 v[62:63], v[236:237], v[230:231], v[62:63] op_sel_hi:[0,1,1]
	v_add_f32_dpp v64, v64, v64 quad_perm:[2,3,0,1] row_mask:0xf bank_mask:0xf bound_ctrl:1
	ds_read_b128 v[220:223], v72 offset:31744
	ds_read_b128 v[216:219], v72 offset:31488
	v_add_f32_dpp v64, v64, v64 row_half_mirror row_mask:0xf bank_mask:0xf bound_ctrl:1
	ds_read_b128 v[228:231], v72 offset:32256
	ds_read_b32 v236, v73 offset:32768
	v_add_f32_dpp v64, v64, v64 row_mirror row_mask:0xf bank_mask:0xf bound_ctrl:1
	v_pk_fma_f32 v[60:61], v[224:225], v[64:65], v[60:61] op_sel_hi:[1,0,1] neg_lo:[1,0,0] neg_hi:[1,0,0]
	v_pk_fma_f32 v[62:63], v[226:227], v[64:65], v[62:63] op_sel_hi:[1,0,1] neg_lo:[1,0,0] neg_hi:[1,0,0]
	ds_read_b128 v[224:227], v72 offset:32000
	v_pk_mul_f32 v[66:67], v[232:233], v[60:61]
	v_pk_fma_f32 v[66:67], v[234:235], v[62:63], v[66:67]
	ds_read_b128 v[232:235], v72 offset:32512
	v_add_f32_e32 v142, v66, v67
	s_waitcnt lgkmcnt(6)
	v_pk_mul_f32 v[64:65], v[60:61], v[122:123]
	v_pk_fma_f32 v[64:65], v[62:63], v[124:125], v[64:65]
	v_add_f32_e32 v64, v64, v65
	v_pk_mul_f32 v[60:61], v[60:61], v[118:119]
	v_pk_mul_f32 v[62:63], v[62:63], v[120:121]
	v_add_f32_dpp v64, v64, v64 quad_perm:[1,0,3,2] row_mask:0xf bank_mask:0xf bound_ctrl:1
	v_pk_fma_f32 v[60:61], v[138:139], v[130:131], v[60:61] op_sel_hi:[0,1,1]
	v_pk_fma_f32 v[62:63], v[138:139], v[132:133], v[62:63] op_sel_hi:[0,1,1]
	v_add_f32_dpp v64, v64, v64 quad_perm:[2,3,0,1] row_mask:0xf bank_mask:0xf bound_ctrl:1
	ds_read_b128 v[122:125], v72 offset:33280
	ds_read_b128 v[118:121], v72 offset:33024
	v_add_f32_dpp v64, v64, v64 row_half_mirror row_mask:0xf bank_mask:0xf bound_ctrl:1
	ds_read_b128 v[130:133], v72 offset:33792
	ds_read_b32 v138, v73 offset:34304
	v_add_f32_dpp v64, v64, v64 row_mirror row_mask:0xf bank_mask:0xf bound_ctrl:1
	v_pk_fma_f32 v[60:61], v[126:127], v[64:65], v[60:61] op_sel_hi:[1,0,1] neg_lo:[1,0,0] neg_hi:[1,0,0]
	v_pk_fma_f32 v[62:63], v[128:129], v[64:65], v[62:63] op_sel_hi:[1,0,1] neg_lo:[1,0,0] neg_hi:[1,0,0]
	ds_read_b128 v[126:129], v72 offset:33536
	v_pk_mul_f32 v[66:67], v[134:135], v[60:61]
	v_pk_fma_f32 v[66:67], v[136:137], v[62:63], v[66:67]
	ds_read_b128 v[134:137], v72 offset:34048
	v_add_f32_e32 v143, v66, v67
	s_waitcnt lgkmcnt(6)
; template <bool DUAL>
; __device__ __forceinline__ void rwkv_tile(const Params& p, int l, int tile, unsigned char* smem) {
;     ...
; #pragma unroll 2
;       for (int i = 0; i < 32; ++i) {
;         const int inx = (i + 1) & 31;
;         const float4 nw4 = *(const float4*)(rp + inx * 384), nkk4 = *(const float4*)(rp + inx * 384 + 64), nkb4 = *(const float4*)(rp + inx * 384 + 128);
;         const float4 nkd4 = *(const float4*)(rp + inx * 384 + 192), nr4 = *(const float4*)(rp + inx * 384 + 256);
;         const float nv = vp[inx * 384];
;         v2f t = sA * (v2f){kk4.x, kk4.y};
;         t = sB * (v2f){kk4.z, kk4.w} + t;
;         float sa = t.x + t.y, ia = 0.f;
;         if (DUAL) {
;           v2f ti = iA * (v2f){kk4.x, kk4.y};
;           ti = iB * (v2f){kk4.z, kk4.w} + ti;
;           ia = ti.x + ti.y;
;           sa += dppf<0xB1>(sa); ia += dppf<0xB1>(ia);
;           sa += dppf<0x4E>(sa); ia += dppf<0x4E>(ia);
;           sa += dppf<0x141>(sa); ia += dppf<0x141>(ia);
;           sa += dppf<0x140>(sa); ia += dppf<0x140>(ia);
;         } else {
;           sa = sum16(sa);
;         }
;         v2f cA = sA * (v2f){w4.x, w4.y} + (v2f){kd4.x, kd4.y} * v;
;         v2f cB = sB * (v2f){w4.z, w4.w} + (v2f){kd4.z, kd4.w} * v;
;         sA = cA - (v2f){kb4.x, kb4.y} * sa;
;         sB = cB - (v2f){kb4.z, kb4.w} * sa;
;         v2f u = sA * (v2f){r4.x, r4.y};
;         u = sB * (v2f){r4.z, r4.w} + u;
;         float y = u.x + u.y, g = 0.f;
;         if (DUAL) {
;           iA = iA * (v2f){w4.x, w4.y} - (v2f){kb4.x, kb4.y} * ia;
;           iB = iB * (v2f){w4.z, w4.w} - (v2f){kb4.z, kb4.w} * ia;
;           v2f ui = iA * (v2f){r4.x, r4.y};
;           ui = iB * (v2f){r4.z, r4.w} + ui;
;           g = ui.x + ui.y;
;           y += dppf<0xB1>(y); g += dppf<0xB1>(g);
;           y += dppf<0x4E>(y); g += dppf<0x4E>(g);
;           y += dppf<0x141>(y); g += dppf<0x141>(g);
;           y += dppf<0x140>(y); g += dppf<0x140>(g);
;           if (fr == (i & 15)) gkeep = g;
;         } else {
;           y = sum16(y);
;         }
;         if (fr == (i & 15)) ykeep = y;
	v_pk_mul_f32 v[64:65], v[60:61], v[220:221]
	v_pk_fma_f32 v[64:65], v[62:63], v[222:223], v[64:65]
	v_add_f32_e32 v64, v64, v65
	v_pk_mul_f32 v[60:61], v[60:61], v[216:217]
	v_pk_mul_f32 v[62:63], v[62:63], v[218:219]
	v_add_f32_dpp v64, v64, v64 quad_perm:[1,0,3,2] row_mask:0xf bank_mask:0xf bound_ctrl:1
	v_pk_fma_f32 v[60:61], v[236:237], v[228:229], v[60:61] op_sel_hi:[0,1,1]
	v_pk_fma_f32 v[62:63], v[236:237], v[230:231], v[62:63] op_sel_hi:[0,1,1]
	v_add_f32_dpp v64, v64, v64 quad_perm:[2,3,0,1] row_mask:0xf bank_mask:0xf bound_ctrl:1
	ds_read_b128 v[220:223], v72 offset:34816
	ds_read_b128 v[216:219], v72 offset:34560
	v_add_f32_dpp v64, v64, v64 row_half_mirror row_mask:0xf bank_mask:0xf bound_ctrl:1
	ds_read_b128 v[228:231], v72 offset:35328
	ds_read_b32 v236, v73 offset:35840
	v_add_f32_dpp v64, v64, v64 row_mirror row_mask:0xf bank_mask:0xf bound_ctrl:1
	v_pk_fma_f32 v[60:61], v[224:225], v[64:65], v[60:61] op_sel_hi:[1,0,1] neg_lo:[1,0,0] neg_hi:[1,0,0]
	v_pk_fma_f32 v[62:63], v[226:227], v[64:65], v[62:63] op_sel_hi:[1,0,1] neg_lo:[1,0,0] neg_hi:[1,0,0]
	ds_read_b128 v[224:227], v72 offset:35072
	v_pk_mul_f32 v[66:67], v[232:233], v[60:61]
	v_pk_fma_f32 v[66:67], v[234:235], v[62:63], v[66:67]
	ds_read_b128 v[232:235], v72 offset:35584
	v_add_f32_e32 v144, v66, v67
	s_waitcnt lgkmcnt(6)
	v_pk_mul_f32 v[64:65], v[60:61], v[122:123]
	v_pk_fma_f32 v[64:65], v[62:63], v[124:125], v[64:65]
	v_add_f32_e32 v64, v64, v65
	v_pk_mul_f32 v[60:61], v[60:61], v[118:119]
	v_pk_mul_f32 v[62:63], v[62:63], v[120:121]
	v_add_f32_dpp v64, v64, v64 quad_perm:[1,0,3,2] row_mask:0xf bank_mask:0xf bound_ctrl:1
	v_pk_fma_f32 v[60:61], v[138:139], v[130:131], v[60:61] op_sel_hi:[0,1,1]
	v_pk_fma_f32 v[62:63], v[138:139], v[132:133], v[62:63] op_sel_hi:[0,1,1]
	v_add_f32_dpp v64, v64, v64 quad_perm:[2,3,0,1] row_mask:0xf bank_mask:0xf bound_ctrl:1
	ds_read_b128 v[122:125], v72 offset:36352
	ds_read_b128 v[118:121], v72 offset:36096
	v_add_f32_dpp v64, v64, v64 row_half_mirror row_mask:0xf bank_mask:0xf bound_ctrl:1
	ds_read_b128 v[130:133], v72 offset:36864
	ds_read_b32 v138, v73 offset:37376
	v_add_f32_dpp v64, v64, v64 row_mirror row_mask:0xf bank_mask:0xf bound_ctrl:1
	v_pk_fma_f32 v[60:61], v[126:127], v[64:65], v[60:61] op_sel_hi:[1,0,1] neg_lo:[1,0,0] neg_hi:[1,0,0]
	v_pk_fma_f32 v[62:63], v[128:129], v[64:65], v[62:63] op_sel_hi:[1,0,1] neg_lo:[1,0,0] neg_hi:[1,0,0]
	ds_read_b128 v[126:129], v72 offset:36608
	v_pk_mul_f32 v[66:67], v[134:135], v[60:61]
	v_pk_fma_f32 v[66:67], v[136:137], v[62:63], v[66:67]
	ds_read_b128 v[134:137], v72 offset:37120
	v_add_f32_e32 v145, v66, v67
	s_waitcnt lgkmcnt(6)
	v_pk_mul_f32 v[64:65], v[60:61], v[220:221]
	v_pk_fma_f32 v[64:65], v[62:63], v[222:223], v[64:65]
	v_add_f32_e32 v64, v64, v65
	v_pk_mul_f32 v[60:61], v[60:61], v[216:217]
	v_pk_mul_f32 v[62:63], v[62:63], v[218:219]
	v_add_f32_dpp v64, v64, v64 quad_perm:[1,0,3,2] row_mask:0xf bank_mask:0xf bound_ctrl:1
	v_pk_fma_f32 v[60:61], v[236:237], v[228:229], v[60:61] op_sel_hi:[0,1,1]
	v_pk_fma_f32 v[62:63], v[236:237], v[230:231], v[62:63] op_sel_hi:[0,1,1]
	v_add_f32_dpp v64, v64, v64 quad_perm:[2,3,0,1] row_mask:0xf bank_mask:0xf bound_ctrl:1
	ds_read_b128 v[220:223], v72 offset:37888
	ds_read_b128 v[216:219], v72 offset:37632
	v_add_f32_dpp v64, v64, v64 row_half_mirror row_mask:0xf bank_mask:0xf bound_ctrl:1
	ds_read_b128 v[228:231], v72 offset:38400
	ds_read_b32 v236, v73 offset:38912
	v_add_f32_dpp v64, v64, v64 row_mirror row_mask:0xf bank_mask:0xf bound_ctrl:1
	v_pk_fma_f32 v[60:61], v[224:225], v[64:65], v[60:61] op_sel_hi:[1,0,1] neg_lo:[1,0,0] neg_hi:[1,0,0]
	v_pk_fma_f32 v[62:63], v[226:227], v[64:65], v[62:63] op_sel_hi:[1,0,1] neg_lo:[1,0,0] neg_hi:[1,0,0]
	ds_read_b128 v[224:227], v72 offset:38144
	v_pk_mul_f32 v[66:67], v[232:233], v[60:61]
	v_pk_fma_f32 v[66:67], v[234:235], v[62:63], v[66:67]
	ds_read_b128 v[232:235], v72 offset:38656
	v_add_f32_e32 v146, v66, v67
	s_waitcnt lgkmcnt(6)
	v_pk_mul_f32 v[64:65], v[60:61], v[122:123]
	v_pk_fma_f32 v[64:65], v[62:63], v[124:125], v[64:65]
	v_add_f32_e32 v64, v64, v65
	v_pk_mul_f32 v[60:61], v[60:61], v[118:119]
	v_pk_mul_f32 v[62:63], v[62:63], v[120:121]
	v_add_f32_dpp v64, v64, v64 quad_perm:[1,0,3,2] row_mask:0xf bank_mask:0xf bound_ctrl:1
	v_pk_fma_f32 v[60:61], v[138:139], v[130:131], v[60:61] op_sel_hi:[0,1,1]
	v_pk_fma_f32 v[62:63], v[138:139], v[132:133], v[62:63] op_sel_hi:[0,1,1]
	v_add_f32_dpp v64, v64, v64 quad_perm:[2,3,0,1] row_mask:0xf bank_mask:0xf bound_ctrl:1
	ds_read_b128 v[122:125], v72 offset:39424
	ds_read_b128 v[118:121], v72 offset:39168
	v_add_f32_dpp v64, v64, v64 row_half_mirror row_mask:0xf bank_mask:0xf bound_ctrl:1
	ds_read_b128 v[130:133], v72 offset:39936
	ds_read_b32 v138, v73 offset:40448
	v_add_f32_dpp v64, v64, v64 row_mirror row_mask:0xf bank_mask:0xf bound_ctrl:1
	v_pk_fma_f32 v[60:61], v[126:127], v[64:65], v[60:61] op_sel_hi:[1,0,1] neg_lo:[1,0,0] neg_hi:[1,0,0]
	v_pk_fma_f32 v[62:63], v[128:129], v[64:65], v[62:63] op_sel_hi:[1,0,1] neg_lo:[1,0,0] neg_hi:[1,0,0]
	ds_read_b128 v[126:129], v72 offset:39680
	v_pk_mul_f32 v[66:67], v[134:135], v[60:61]
	v_pk_fma_f32 v[66:67], v[136:137], v[62:63], v[66:67]
	ds_read_b128 v[134:137], v72 offset:40192
	v_add_f32_e32 v147, v66, v67
	s_waitcnt lgkmcnt(6)
; template <bool DUAL>
; __device__ __forceinline__ void rwkv_tile(const Params& p, int l, int tile, unsigned char* smem) {
;     ...
; #pragma unroll 2
;       for (int i = 0; i < 32; ++i) {
;         const int inx = (i + 1) & 31;
;         const float4 nw4 = *(const float4*)(rp + inx * 384), nkk4 = *(const float4*)(rp + inx * 384 + 64), nkb4 = *(const float4*)(rp + inx * 384 + 128);
;         const float4 nkd4 = *(const float4*)(rp + inx * 384 + 192), nr4 = *(const float4*)(rp + inx * 384 + 256);
;         const float nv = vp[inx * 384];
;         v2f t = sA * (v2f){kk4.x, kk4.y};
;         t = sB * (v2f){kk4.z, kk4.w} + t;
;         float sa = t.x + t.y, ia = 0.f;
;         if (DUAL) {
;           v2f ti = iA * (v2f){kk4.x, kk4.y};
;           ti = iB * (v2f){kk4.z, kk4.w} + ti;
;           ia = ti.x + ti.y;
;           sa += dppf<0xB1>(sa); ia += dppf<0xB1>(ia);
;           sa += dppf<0x4E>(sa); ia += dppf<0x4E>(ia);
;           sa += dppf<0x141>(sa); ia += dppf<0x141>(ia);
;           sa += dppf<0x140>(sa); ia += dppf<0x140>(ia);
;         } else {
;           sa = sum16(sa);
;         }
;         v2f cA = sA * (v2f){w4.x, w4.y} + (v2f){kd4.x, kd4.y} * v;
;         v2f cB = sB * (v2f){w4.z, w4.w} + (v2f){kd4.z, kd4.w} * v;
;         sA = cA - (v2f){kb4.x, kb4.y} * sa;
;         sB = cB - (v2f){kb4.z, kb4.w} * sa;
;         v2f u = sA * (v2f){r4.x, r4.y};
;         u = sB * (v2f){r4.z, r4.w} + u;
;         float y = u.x + u.y, g = 0.f;
;         if (DUAL) {
;           iA = iA * (v2f){w4.x, w4.y} - (v2f){kb4.x, kb4.y} * ia;
;           iB = iB * (v2f){w4.z, w4.w} - (v2f){kb4.z, kb4.w} * ia;
;           v2f ui = iA * (v2f){r4.x, r4.y};
;           ui = iB * (v2f){r4.z, r4.w} + ui;
;           g = ui.x + ui.y;
;           y += dppf<0xB1>(y); g += dppf<0xB1>(g);
;           y += dppf<0x4E>(y); g += dppf<0x4E>(g);
;           y += dppf<0x141>(y); g += dppf<0x141>(g);
;           y += dppf<0x140>(y); g += dppf<0x140>(g);
;           if (fr == (i & 15)) gkeep = g;
;         } else {
;           y = sum16(y);
;         }
;         if (fr == (i & 15)) ykeep = y;
	v_pk_mul_f32 v[64:65], v[60:61], v[220:221]
	v_pk_fma_f32 v[64:65], v[62:63], v[222:223], v[64:65]
	v_add_f32_e32 v64, v64, v65
	v_pk_mul_f32 v[60:61], v[60:61], v[216:217]
	v_pk_mul_f32 v[62:63], v[62:63], v[218:219]
	v_add_f32_dpp v64, v64, v64 quad_perm:[1,0,3,2] row_mask:0xf bank_mask:0xf bound_ctrl:1
	v_pk_fma_f32 v[60:61], v[236:237], v[228:229], v[60:61] op_sel_hi:[0,1,1]
	v_pk_fma_f32 v[62:63], v[236:237], v[230:231], v[62:63] op_sel_hi:[0,1,1]
	v_add_f32_dpp v64, v64, v64 quad_perm:[2,3,0,1] row_mask:0xf bank_mask:0xf bound_ctrl:1
	ds_read_b128 v[220:223], v72 offset:40960
	ds_read_b128 v[216:219], v72 offset:40704
	v_add_f32_dpp v64, v64, v64 row_half_mirror row_mask:0xf bank_mask:0xf bound_ctrl:1
	ds_read_b128 v[228:231], v72 offset:41472
	ds_read_b32 v236, v73 offset:41984
	v_add_f32_dpp v64, v64, v64 row_mirror row_mask:0xf bank_mask:0xf bound_ctrl:1
	v_pk_fma_f32 v[60:61], v[224:225], v[64:65], v[60:61] op_sel_hi:[1,0,1] neg_lo:[1,0,0] neg_hi:[1,0,0]
	v_pk_fma_f32 v[62:63], v[226:227], v[64:65], v[62:63] op_sel_hi:[1,0,1] neg_lo:[1,0,0] neg_hi:[1,0,0]
	ds_read_b128 v[224:227], v72 offset:41216
	v_pk_mul_f32 v[66:67], v[232:233], v[60:61]
	v_pk_fma_f32 v[66:67], v[234:235], v[62:63], v[66:67]
	ds_read_b128 v[232:235], v72 offset:41728
	v_add_f32_e32 v148, v66, v67
	s_waitcnt lgkmcnt(6)
	v_pk_mul_f32 v[64:65], v[60:61], v[122:123]
	v_pk_fma_f32 v[64:65], v[62:63], v[124:125], v[64:65]
	v_add_f32_e32 v64, v64, v65
	v_pk_mul_f32 v[60:61], v[60:61], v[118:119]
	v_pk_mul_f32 v[62:63], v[62:63], v[120:121]
	v_add_f32_dpp v64, v64, v64 quad_perm:[1,0,3,2] row_mask:0xf bank_mask:0xf bound_ctrl:1
	v_pk_fma_f32 v[60:61], v[138:139], v[130:131], v[60:61] op_sel_hi:[0,1,1]
	v_pk_fma_f32 v[62:63], v[138:139], v[132:133], v[62:63] op_sel_hi:[0,1,1]
	v_add_f32_dpp v64, v64, v64 quad_perm:[2,3,0,1] row_mask:0xf bank_mask:0xf bound_ctrl:1
	ds_read_b128 v[122:125], v72 offset:42496
	ds_read_b128 v[118:121], v72 offset:42240
	v_add_f32_dpp v64, v64, v64 row_half_mirror row_mask:0xf bank_mask:0xf bound_ctrl:1
	ds_read_b128 v[130:133], v72 offset:43008
	ds_read_b32 v138, v73 offset:43520
	v_add_f32_dpp v64, v64, v64 row_mirror row_mask:0xf bank_mask:0xf bound_ctrl:1
	v_pk_fma_f32 v[60:61], v[126:127], v[64:65], v[60:61] op_sel_hi:[1,0,1] neg_lo:[1,0,0] neg_hi:[1,0,0]
	v_pk_fma_f32 v[62:63], v[128:129], v[64:65], v[62:63] op_sel_hi:[1,0,1] neg_lo:[1,0,0] neg_hi:[1,0,0]
	ds_read_b128 v[126:129], v72 offset:42752
	v_pk_mul_f32 v[66:67], v[134:135], v[60:61]
	v_pk_fma_f32 v[66:67], v[136:137], v[62:63], v[66:67]
	ds_read_b128 v[134:137], v72 offset:43264
	v_add_f32_e32 v149, v66, v67
	s_waitcnt lgkmcnt(6)
	v_pk_mul_f32 v[64:65], v[60:61], v[220:221]
	v_pk_fma_f32 v[64:65], v[62:63], v[222:223], v[64:65]
	v_add_f32_e32 v64, v64, v65
	v_pk_mul_f32 v[60:61], v[60:61], v[216:217]
	v_pk_mul_f32 v[62:63], v[62:63], v[218:219]
	v_add_f32_dpp v64, v64, v64 quad_perm:[1,0,3,2] row_mask:0xf bank_mask:0xf bound_ctrl:1
	v_pk_fma_f32 v[60:61], v[236:237], v[228:229], v[60:61] op_sel_hi:[0,1,1]
	v_pk_fma_f32 v[62:63], v[236:237], v[230:231], v[62:63] op_sel_hi:[0,1,1]
	v_add_f32_dpp v64, v64, v64 quad_perm:[2,3,0,1] row_mask:0xf bank_mask:0xf bound_ctrl:1
	ds_read_b128 v[220:223], v72 offset:44032
	ds_read_b128 v[216:219], v72 offset:43776
	v_add_f32_dpp v64, v64, v64 row_half_mirror row_mask:0xf bank_mask:0xf bound_ctrl:1
	ds_read_b128 v[228:231], v72 offset:44544
	ds_read_b32 v236, v73 offset:45056
	v_add_f32_dpp v64, v64, v64 row_mirror row_mask:0xf bank_mask:0xf bound_ctrl:1
	v_pk_fma_f32 v[60:61], v[224:225], v[64:65], v[60:61] op_sel_hi:[1,0,1] neg_lo:[1,0,0] neg_hi:[1,0,0]
	v_pk_fma_f32 v[62:63], v[226:227], v[64:65], v[62:63] op_sel_hi:[1,0,1] neg_lo:[1,0,0] neg_hi:[1,0,0]
	ds_read_b128 v[224:227], v72 offset:44288
	v_pk_mul_f32 v[66:67], v[232:233], v[60:61]
	v_pk_fma_f32 v[66:67], v[234:235], v[62:63], v[66:67]
	ds_read_b128 v[232:235], v72 offset:44800
	v_add_f32_e32 v150, v66, v67
	s_waitcnt lgkmcnt(6)
	v_pk_mul_f32 v[64:65], v[60:61], v[122:123]
	v_pk_fma_f32 v[64:65], v[62:63], v[124:125], v[64:65]
	v_add_f32_e32 v64, v64, v65
	v_pk_mul_f32 v[60:61], v[60:61], v[118:119]
	v_pk_mul_f32 v[62:63], v[62:63], v[120:121]
	v_add_f32_dpp v64, v64, v64 quad_perm:[1,0,3,2] row_mask:0xf bank_mask:0xf bound_ctrl:1
	v_pk_fma_f32 v[60:61], v[138:139], v[130:131], v[60:61] op_sel_hi:[0,1,1]
	v_pk_fma_f32 v[62:63], v[138:139], v[132:133], v[62:63] op_sel_hi:[0,1,1]
	v_add_f32_dpp v64, v64, v64 quad_perm:[2,3,0,1] row_mask:0xf bank_mask:0xf bound_ctrl:1
	ds_read_b128 v[122:125], v72 offset:45568
	ds_read_b128 v[118:121], v72 offset:45312
	v_add_f32_dpp v64, v64, v64 row_half_mirror row_mask:0xf bank_mask:0xf bound_ctrl:1
	ds_read_b128 v[130:133], v72 offset:46080
	ds_read_b32 v138, v73 offset:46592
	v_add_f32_dpp v64, v64, v64 row_mirror row_mask:0xf bank_mask:0xf bound_ctrl:1
	v_pk_fma_f32 v[60:61], v[126:127], v[64:65], v[60:61] op_sel_hi:[1,0,1] neg_lo:[1,0,0] neg_hi:[1,0,0]
	v_pk_fma_f32 v[62:63], v[128:129], v[64:65], v[62:63] op_sel_hi:[1,0,1] neg_lo:[1,0,0] neg_hi:[1,0,0]
	ds_read_b128 v[126:129], v72 offset:45824
	v_pk_mul_f32 v[66:67], v[134:135], v[60:61]
	v_pk_fma_f32 v[66:67], v[136:137], v[62:63], v[66:67]
	ds_read_b128 v[134:137], v72 offset:46336
	v_add_f32_e32 v151, v66, v67
	s_waitcnt lgkmcnt(6)
; template <bool DUAL>
; __device__ __forceinline__ void rwkv_tile(const Params& p, int l, int tile, unsigned char* smem) {
;     ...
; #pragma unroll 2
;       for (int i = 0; i < 32; ++i) {
;         const int inx = (i + 1) & 31;
;         const float4 nw4 = *(const float4*)(rp + inx * 384), nkk4 = *(const float4*)(rp + inx * 384 + 64), nkb4 = *(const float4*)(rp + inx * 384 + 128);
;         const float4 nkd4 = *(const float4*)(rp + inx * 384 + 192), nr4 = *(const float4*)(rp + inx * 384 + 256);
;         const float nv = vp[inx * 384];
;         v2f t = sA * (v2f){kk4.x, kk4.y};
;         t = sB * (v2f){kk4.z, kk4.w} + t;
;         float sa = t.x + t.y, ia = 0.f;
;         if (DUAL) {
;           v2f ti = iA * (v2f){kk4.x, kk4.y};
;           ti = iB * (v2f){kk4.z, kk4.w} + ti;
;           ia = ti.x + ti.y;
;           sa += dppf<0xB1>(sa); ia += dppf<0xB1>(ia);
;           sa += dppf<0x4E>(sa); ia += dppf<0x4E>(ia);
;           sa += dppf<0x141>(sa); ia += dppf<0x141>(ia);
;           sa += dppf<0x140>(sa); ia += dppf<0x140>(ia);
;         } else {
;           sa = sum16(sa);
;         }
;         v2f cA = sA * (v2f){w4.x, w4.y} + (v2f){kd4.x, kd4.y} * v;
;         v2f cB = sB * (v2f){w4.z, w4.w} + (v2f){kd4.z, kd4.w} * v;
;         sA = cA - (v2f){kb4.x, kb4.y} * sa;
;         sB = cB - (v2f){kb4.z, kb4.w} * sa;
;         v2f u = sA * (v2f){r4.x, r4.y};
;         u = sB * (v2f){r4.z, r4.w} + u;
;         float y = u.x + u.y, g = 0.f;
;         if (DUAL) {
;           iA = iA * (v2f){w4.x, w4.y} - (v2f){kb4.x, kb4.y} * ia;
;           iB = iB * (v2f){w4.z, w4.w} - (v2f){kb4.z, kb4.w} * ia;
;           v2f ui = iA * (v2f){r4.x, r4.y};
;           ui = iB * (v2f){r4.z, r4.w} + ui;
;           g = ui.x + ui.y;
;           y += dppf<0xB1>(y); g += dppf<0xB1>(g);
;           y += dppf<0x4E>(y); g += dppf<0x4E>(g);
;           y += dppf<0x141>(y); g += dppf<0x141>(g);
;           y += dppf<0x140>(y); g += dppf<0x140>(g);
;           if (fr == (i & 15)) gkeep = g;
;         } else {
;           y = sum16(y);
;         }
;         if (fr == (i & 15)) ykeep = y;
	v_pk_mul_f32 v[64:65], v[60:61], v[220:221]
	v_pk_fma_f32 v[64:65], v[62:63], v[222:223], v[64:65]
	v_add_f32_e32 v64, v64, v65
	v_pk_mul_f32 v[60:61], v[60:61], v[216:217]
	v_pk_mul_f32 v[62:63], v[62:63], v[218:219]
	v_add_f32_dpp v64, v64, v64 quad_perm:[1,0,3,2] row_mask:0xf bank_mask:0xf bound_ctrl:1
	v_pk_fma_f32 v[60:61], v[236:237], v[228:229], v[60:61] op_sel_hi:[0,1,1]
	v_pk_fma_f32 v[62:63], v[236:237], v[230:231], v[62:63] op_sel_hi:[0,1,1]
	v_add_f32_dpp v64, v64, v64 quad_perm:[2,3,0,1] row_mask:0xf bank_mask:0xf bound_ctrl:1
	ds_read_b128 v[220:223], v72 offset:47104
	ds_read_b128 v[216:219], v72 offset:46848
	v_add_f32_dpp v64, v64, v64 row_half_mirror row_mask:0xf bank_mask:0xf bound_ctrl:1
	ds_read_b128 v[228:231], v72 offset:47616
	ds_read_b32 v236, v73 offset:48128
	v_add_f32_dpp v64, v64, v64 row_mirror row_mask:0xf bank_mask:0xf bound_ctrl:1
	v_pk_fma_f32 v[60:61], v[224:225], v[64:65], v[60:61] op_sel_hi:[1,0,1] neg_lo:[1,0,0] neg_hi:[1,0,0]
	v_pk_fma_f32 v[62:63], v[226:227], v[64:65], v[62:63] op_sel_hi:[1,0,1] neg_lo:[1,0,0] neg_hi:[1,0,0]
	ds_read_b128 v[224:227], v72 offset:47360
	v_pk_mul_f32 v[66:67], v[232:233], v[60:61]
	v_pk_fma_f32 v[66:67], v[234:235], v[62:63], v[66:67]
	ds_read_b128 v[232:235], v72 offset:47872
	v_add_f32_e32 v152, v66, v67
	s_waitcnt lgkmcnt(6)
	v_pk_mul_f32 v[64:65], v[60:61], v[122:123]
	v_pk_fma_f32 v[64:65], v[62:63], v[124:125], v[64:65]
	v_add_f32_e32 v64, v64, v65
	v_pk_mul_f32 v[60:61], v[60:61], v[118:119]
	v_pk_mul_f32 v[62:63], v[62:63], v[120:121]
	v_add_f32_dpp v64, v64, v64 quad_perm:[1,0,3,2] row_mask:0xf bank_mask:0xf bound_ctrl:1
	v_pk_fma_f32 v[60:61], v[138:139], v[130:131], v[60:61] op_sel_hi:[0,1,1]
	v_pk_fma_f32 v[62:63], v[138:139], v[132:133], v[62:63] op_sel_hi:[0,1,1]
	v_add_f32_dpp v64, v64, v64 quad_perm:[2,3,0,1] row_mask:0xf bank_mask:0xf bound_ctrl:1
	ds_read_b128 v[122:125], v72 offset:48640
	ds_read_b128 v[118:121], v72 offset:48384
	v_add_f32_dpp v64, v64, v64 row_half_mirror row_mask:0xf bank_mask:0xf bound_ctrl:1
	ds_read_b128 v[130:133], v72 offset:49152
	ds_read_b32 v138, v73 offset:49664
	v_add_f32_dpp v64, v64, v64 row_mirror row_mask:0xf bank_mask:0xf bound_ctrl:1
	v_pk_fma_f32 v[60:61], v[126:127], v[64:65], v[60:61] op_sel_hi:[1,0,1] neg_lo:[1,0,0] neg_hi:[1,0,0]
	v_pk_fma_f32 v[62:63], v[128:129], v[64:65], v[62:63] op_sel_hi:[1,0,1] neg_lo:[1,0,0] neg_hi:[1,0,0]
	ds_read_b128 v[126:129], v72 offset:48896
	v_pk_mul_f32 v[66:67], v[134:135], v[60:61]
	v_pk_fma_f32 v[66:67], v[136:137], v[62:63], v[66:67]
	ds_read_b128 v[134:137], v72 offset:49408
	v_add_f32_e32 v153, v66, v67
	s_waitcnt lgkmcnt(6)
	v_pk_mul_f32 v[64:65], v[60:61], v[220:221]
	v_pk_fma_f32 v[64:65], v[62:63], v[222:223], v[64:65]
	v_add_f32_e32 v64, v64, v65
	v_pk_mul_f32 v[60:61], v[60:61], v[216:217]
	v_pk_mul_f32 v[62:63], v[62:63], v[218:219]
	v_add_f32_dpp v64, v64, v64 quad_perm:[1,0,3,2] row_mask:0xf bank_mask:0xf bound_ctrl:1
	v_pk_fma_f32 v[60:61], v[236:237], v[228:229], v[60:61] op_sel_hi:[0,1,1]
	v_pk_fma_f32 v[62:63], v[236:237], v[230:231], v[62:63] op_sel_hi:[0,1,1]
	v_add_f32_dpp v64, v64, v64 quad_perm:[2,3,0,1] row_mask:0xf bank_mask:0xf bound_ctrl:1
	ds_read_b128 v[220:223], v68 offset:25600
	ds_read_b128 v[216:219], v68 offset:25344
	v_add_f32_dpp v64, v64, v64 row_half_mirror row_mask:0xf bank_mask:0xf bound_ctrl:1
	ds_read_b128 v[228:231], v68 offset:26112
	ds_read_b32 v236, v69 offset:26624
	v_add_f32_dpp v64, v64, v64 row_mirror row_mask:0xf bank_mask:0xf bound_ctrl:1
	v_pk_fma_f32 v[60:61], v[224:225], v[64:65], v[60:61] op_sel_hi:[1,0,1] neg_lo:[1,0,0] neg_hi:[1,0,0]
	v_pk_fma_f32 v[62:63], v[226:227], v[64:65], v[62:63] op_sel_hi:[1,0,1] neg_lo:[1,0,0] neg_hi:[1,0,0]
	ds_read_b128 v[224:227], v68 offset:25856
	v_pk_mul_f32 v[66:67], v[232:233], v[60:61]
	v_pk_fma_f32 v[66:67], v[234:235], v[62:63], v[66:67]
	ds_read_b128 v[232:235], v68 offset:26368
	v_add_f32_e32 v154, v66, v67
	s_waitcnt lgkmcnt(6)
; __device__ __forceinline__ bf16_t f2bf(float f) { return (bf16_t)(pack2(f, 0.f) & 0xffffu); }
; template <bool DUAL>
; __device__ __forceinline__ void rwkv_tile(const Params& p, int l, int tile, unsigned char* smem) {
;     ...
;           sa = sum16(sa);
;         }
;         v2f cA = sA * (v2f){w4.x, w4.y} + (v2f){kd4.x, kd4.y} * v;
;         v2f cB = sB * (v2f){w4.z, w4.w} + (v2f){kd4.z, kd4.w} * v;
;         sA = cA - (v2f){kb4.x, kb4.y} * sa;
;         sB = cB - (v2f){kb4.z, kb4.w} * sa;
;         v2f u = sA * (v2f){r4.x, r4.y};
;         u = sB * (v2f){r4.z, r4.w} + u;
;         float y = u.x + u.y, g = 0.f;
;         if (DUAL) {
;           iA = iA * (v2f){w4.x, w4.y} - (v2f){kb4.x, kb4.y} * ia;
;           iB = iB * (v2f){w4.z, w4.w} - (v2f){kb4.z, kb4.w} * ia;
;           v2f ui = iA * (v2f){r4.x, r4.y};
;           ui = iB * (v2f){r4.z, r4.w} + ui;
;           g = ui.x + ui.y;
;           y += dppf<0xB1>(y); g += dppf<0xB1>(g);
;           y += dppf<0x4E>(y); g += dppf<0x4E>(g);
;           y += dppf<0x141>(y); g += dppf<0x141>(g);
;           y += dppf<0x140>(y); g += dppf<0x140>(g);
;           if (fr == (i & 15)) gkeep = g;
;         } else {
;           y = sum16(y);
;         }
;         if (fr == (i & 15)) ykeep = y;
;         if ((i & 15) == 15) {
;           const int ii = (i & 16) + fr;
;           const int ri = (d == 0) ? ii + 1 : 32 - ii;
;           const int pi = plo - 1 + ri;
;           p.yR[((size_t)d * TOK + rowbase + pi) * 256 + h * 64 + row] = f2bf(ykeep);
;           if (DUAL) p.GID[((size_t)(d * 4 + b) * NSEG1 + (cix - CSPLIT) * 32 + ii) * 256 + h * 64 + row] = f2bf(gkeep);
;         }
;         w4 = nw4; kk4 = nkk4; kb4 = nkb4; kd4 = nkd4; r4 = nr4; v = nv;
	v_pk_mul_f32 v[64:65], v[60:61], v[122:123]
	v_pk_fma_f32 v[64:65], v[62:63], v[124:125], v[64:65]
	v_add_f32_e32 v64, v64, v65
	v_pk_mul_f32 v[60:61], v[60:61], v[118:119]
	v_pk_mul_f32 v[62:63], v[62:63], v[120:121]
	v_add_f32_dpp v64, v64, v64 quad_perm:[1,0,3,2] row_mask:0xf bank_mask:0xf bound_ctrl:1
	v_pk_fma_f32 v[60:61], v[138:139], v[130:131], v[60:61] op_sel_hi:[0,1,1]
	v_pk_fma_f32 v[62:63], v[138:139], v[132:133], v[62:63] op_sel_hi:[0,1,1]
	v_add_f32_dpp v64, v64, v64 quad_perm:[2,3,0,1] row_mask:0xf bank_mask:0xf bound_ctrl:1
	ds_read_b128 v[122:125], v68 offset:27136
	ds_read_b128 v[118:121], v68 offset:26880
	v_add_f32_dpp v64, v64, v64 row_half_mirror row_mask:0xf bank_mask:0xf bound_ctrl:1
	ds_read_b128 v[130:133], v68 offset:27648
	ds_read_b32 v138, v69 offset:28160
	v_add_f32_dpp v64, v64, v64 row_mirror row_mask:0xf bank_mask:0xf bound_ctrl:1
	v_pk_fma_f32 v[60:61], v[126:127], v[64:65], v[60:61] op_sel_hi:[1,0,1] neg_lo:[1,0,0] neg_hi:[1,0,0]
	v_pk_fma_f32 v[62:63], v[128:129], v[64:65], v[62:63] op_sel_hi:[1,0,1] neg_lo:[1,0,0] neg_hi:[1,0,0]
	ds_read_b128 v[126:129], v68 offset:27392
	v_pk_mul_f32 v[66:67], v[134:135], v[60:61]
	v_pk_fma_f32 v[66:67], v[136:137], v[62:63], v[66:67]
	ds_read_b128 v[134:137], v68 offset:27904
	v_add_f32_e32 v155, v66, v67
	v_add_f32_dpp v140, v140, v140 row_shl:8 row_mask:0xf bank_mask:0x3
	v_add_f32_dpp v140, v148, v148 row_shr:8 row_mask:0xf bank_mask:0xc
	v_add_f32_dpp v141, v141, v141 row_shl:8 row_mask:0xf bank_mask:0x3
	v_add_f32_dpp v141, v149, v149 row_shr:8 row_mask:0xf bank_mask:0xc
	v_add_f32_dpp v142, v142, v142 row_shl:8 row_mask:0xf bank_mask:0x3
	v_add_f32_dpp v142, v150, v150 row_shr:8 row_mask:0xf bank_mask:0xc
	v_add_f32_dpp v143, v143, v143 row_shl:8 row_mask:0xf bank_mask:0x3
	v_add_f32_dpp v143, v151, v151 row_shr:8 row_mask:0xf bank_mask:0xc
	v_add_f32_dpp v144, v144, v144 row_shl:8 row_mask:0xf bank_mask:0x3
	v_add_f32_dpp v144, v152, v152 row_shr:8 row_mask:0xf bank_mask:0xc
	v_add_f32_dpp v145, v145, v145 row_shl:8 row_mask:0xf bank_mask:0x3
	v_add_f32_dpp v145, v153, v153 row_shr:8 row_mask:0xf bank_mask:0xc
	v_add_f32_dpp v146, v146, v146 row_shl:8 row_mask:0xf bank_mask:0x3
	v_add_f32_dpp v146, v154, v154 row_shr:8 row_mask:0xf bank_mask:0xc
	v_add_f32_dpp v147, v147, v147 row_shl:8 row_mask:0xf bank_mask:0x3
	v_add_f32_dpp v147, v155, v155 row_shr:8 row_mask:0xf bank_mask:0xc
	v_add_f32_dpp v140, v140, v140 row_shl:4 row_mask:0xf bank_mask:0x5
	v_add_f32_dpp v140, v144, v144 row_shr:4 row_mask:0xf bank_mask:0xa
	v_add_f32_dpp v141, v141, v141 row_shl:4 row_mask:0xf bank_mask:0x5
	v_add_f32_dpp v141, v145, v145 row_shr:4 row_mask:0xf bank_mask:0xa
	v_add_f32_dpp v142, v142, v142 row_shl:4 row_mask:0xf bank_mask:0x5
	v_add_f32_dpp v142, v146, v146 row_shr:4 row_mask:0xf bank_mask:0xa
	v_add_f32_dpp v143, v143, v143 row_shl:4 row_mask:0xf bank_mask:0x5
	v_add_f32_dpp v143, v147, v147 row_shr:4 row_mask:0xf bank_mask:0xa
	v_cndmask_b32_e32 v156, v140, v142, vcc
	v_cndmask_b32_e32 v157, v142, v140, vcc
	v_cndmask_b32_e32 v159, v143, v141, vcc
	v_cndmask_b32_e32 v158, v141, v143, vcc
	v_add_f32_dpp v156, v157, v156 quad_perm:[2,3,0,1] row_mask:0xf bank_mask:0xf
	v_add_f32_dpp v158, v159, v158 quad_perm:[2,3,0,1] row_mask:0xf bank_mask:0xf
	v_cndmask_b32_e64 v160, v156, v158, s[58:59]
	v_cndmask_b32_e64 v161, v158, v156, s[58:59]
	v_add_u32_e32 v72, 0x6000, v72
	v_add_u32_e32 v73, 0x6000, v73
	v_add_f32_dpp v70, v161, v160 quad_perm:[1,0,3,2] row_mask:0xf bank_mask:0xf
	v_mov_b32_e32 v68, v99
	v_mov_b32_e32 v69, v100
	v_mov_b32_e32 v77, v71
	v_add_u32_e32 v75, 1, v77
	v_sub_u32_e32 v74, 32, v77
	v_cndmask_b32_e64 v74, v74, v75, s[36:37]
	v_add_u32_e32 v74, s28, v74
	v_ashrrev_i32_e32 v75, 31, v74
	v_lshl_add_u64 v[74:75], s[20:21], 0, v[74:75]
	v_lshlrev_b64 v[74:75], 9, v[74:75]
	v_cvt_pk_bf16_f32 v76, v70, v70
	v_lshl_add_u64 v[74:75], v[90:91], 0, v[74:75]
	global_store_short v[74:75], v76, off
	v_add_u32_e32 v71, 16, v71
	s_add_i32 s50, s50, 1
	s_cmp_lg_u32 s50, 2
	s_cbranch_scc1 .Lrw_nd_loop
	s_branch .LBB0_1491
